# scan: row-pair state layout + y(B) dot interleaved into next step + next v-row read issued early (LDS latency no longer exposed)
# speedup vs baseline: 1.0267x; 1.0175x over previous
.LBB0_415:
	v_swap_b32 v17, v12
	v_swap_b32 v19, v14
	s_waitcnt lgkmcnt(0)
	v_pk_mul_f32 v[132:133], v[16:17], v[32:33] op_sel_hi:[1,0]
	v_pk_fma_f32 v[132:133], v[12:13], v[32:33], v[132:133] op_sel:[0,1,0]
	v_pk_fma_f32 v[132:133], v[18:19], v[34:35], v[132:133] op_sel_hi:[1,0,1]
	v_pk_fma_f32 v[132:133], v[14:15], v[34:35], v[132:133] op_sel:[0,1,0]
	v_pk_fma_f32 v[16:17], v[28:29], v[90:91], v[16:17] op_sel_hi:[0,1,1]
	v_pk_fma_f32 v[12:13], v[28:29], v[90:91], v[12:13] op_sel:[1,0,0]
	v_add_f32_dpp v132, v132, v132 quad_perm:[1,0,3,2] row_mask:0xf bank_mask:0xf bound_ctrl:1
	v_add_f32_dpp v133, v133, v133 quad_perm:[1,0,3,2] row_mask:0xf bank_mask:0xf bound_ctrl:1
	v_pk_fma_f32 v[18:19], v[30:31], v[90:91], v[18:19] op_sel_hi:[0,1,1]
	v_add_f32_dpp v132, v132, v132 quad_perm:[2,3,0,1] row_mask:0xf bank_mask:0xf bound_ctrl:1
	v_add_f32_dpp v133, v133, v133 quad_perm:[2,3,0,1] row_mask:0xf bank_mask:0xf bound_ctrl:1
	v_pk_fma_f32 v[14:15], v[30:31], v[90:91], v[14:15] op_sel:[1,0,0]
	v_add_f32_dpp v132, v132, v132 row_half_mirror row_mask:0xf bank_mask:0xf bound_ctrl:1
	v_add_f32_dpp v133, v133, v133 row_half_mirror row_mask:0xf bank_mask:0xf bound_ctrl:1
	ds_read_b64 v[90:91], v115 offset:20736
	ds_read_b128 v[94:97], v42 offset:12288
	ds_read_b128 v[116:119], v42 offset:16384
	ds_read_b128 v[120:123], v42 offset:8192
	ds_read_b128 v[124:127], v42
	ds_read_b64 v[130:131], v92
	v_add_f32_dpp v132, v132, v132 row_mirror row_mask:0xf bank_mask:0xf bound_ctrl:1
	v_add_f32_dpp v133, v133, v133 row_mirror row_mask:0xf bank_mask:0xf bound_ctrl:1
	v_pk_fma_f32 v[16:17], v[24:25], v[132:133], v[16:17] op_sel_hi:[0,1,1]
	v_pk_fma_f32 v[12:13], v[24:25], v[132:133], v[12:13] op_sel:[1,0,0]
	v_pk_fma_f32 v[18:19], v[26:27], v[132:133], v[18:19] op_sel_hi:[0,1,1]
	v_pk_fma_f32 v[14:15], v[26:27], v[132:133], v[14:15] op_sel:[1,0,0]
	s_waitcnt lgkmcnt(4)
	v_pk_mul_f32 v[132:133], v[16:17], v[94:95] op_sel_hi:[1,0]
	v_pk_mul_f32 v[24:25], v[16:17], v[20:21] op_sel_hi:[1,0]
	v_pk_fma_f32 v[132:133], v[12:13], v[94:95], v[132:133] op_sel:[0,1,0]
	v_pk_fma_f32 v[24:25], v[12:13], v[20:21], v[24:25] op_sel:[0,1,0]
	v_pk_fma_f32 v[132:133], v[18:19], v[96:97], v[132:133] op_sel_hi:[1,0,1]
	v_pk_fma_f32 v[24:25], v[18:19], v[22:23], v[24:25] op_sel_hi:[1,0,1]
	v_pk_fma_f32 v[132:133], v[14:15], v[96:97], v[132:133] op_sel:[0,1,0]
	v_pk_fma_f32 v[24:25], v[14:15], v[22:23], v[24:25] op_sel:[0,1,0]
	v_cvt_pk_f16_f32 v24, v24, v25
	v_add_f32_dpp v132, v132, v132 quad_perm:[1,0,3,2] row_mask:0xf bank_mask:0xf bound_ctrl:1
	v_add_f32_dpp v133, v133, v133 quad_perm:[1,0,3,2] row_mask:0xf bank_mask:0xf bound_ctrl:1
	ds_write_b32 v93, v24
	ds_read_b128 v[32:35], v114 offset:12800
	ds_read_b128 v[24:27], v114 offset:16896
	ds_read_b128 v[28:31], v114 offset:8704
	ds_read_b128 v[20:23], v114 offset:512
	s_waitcnt lgkmcnt(5)
	v_pk_fma_f32 v[16:17], v[120:121], v[130:131], v[16:17] op_sel_hi:[0,1,1]
	v_add_f32_dpp v132, v132, v132 quad_perm:[2,3,0,1] row_mask:0xf bank_mask:0xf bound_ctrl:1
	v_add_f32_dpp v133, v133, v133 quad_perm:[2,3,0,1] row_mask:0xf bank_mask:0xf bound_ctrl:1
	v_pk_fma_f32 v[12:13], v[120:121], v[130:131], v[12:13] op_sel:[1,0,0]
	v_add_f32_dpp v132, v132, v132 row_half_mirror row_mask:0xf bank_mask:0xf bound_ctrl:1
	v_add_f32_dpp v133, v133, v133 row_half_mirror row_mask:0xf bank_mask:0xf bound_ctrl:1
	v_pk_fma_f32 v[18:19], v[122:123], v[130:131], v[18:19] op_sel_hi:[0,1,1]
	v_pk_fma_f32 v[14:15], v[122:123], v[130:131], v[14:15] op_sel:[1,0,0]
	v_add_f32_dpp v132, v132, v132 row_mirror row_mask:0xf bank_mask:0xf bound_ctrl:1
	v_add_f32_dpp v133, v133, v133 row_mirror row_mask:0xf bank_mask:0xf bound_ctrl:1
	v_pk_fma_f32 v[16:17], v[116:117], v[132:133], v[16:17] op_sel_hi:[0,1,1]
	v_pk_fma_f32 v[12:13], v[116:117], v[132:133], v[12:13] op_sel:[1,0,0]
	v_pk_fma_f32 v[18:19], v[118:119], v[132:133], v[18:19] op_sel_hi:[0,1,1]
	v_pk_fma_f32 v[14:15], v[118:119], v[132:133], v[14:15] op_sel:[1,0,0]
	s_waitcnt lgkmcnt(0)
	v_pk_mul_f32 v[132:133], v[16:17], v[32:33] op_sel_hi:[1,0]
	v_pk_mul_f32 v[94:95], v[16:17], v[124:125] op_sel_hi:[1,0]
	v_pk_fma_f32 v[132:133], v[12:13], v[32:33], v[132:133] op_sel:[0,1,0]
	v_pk_fma_f32 v[94:95], v[12:13], v[124:125], v[94:95] op_sel:[0,1,0]
	v_pk_fma_f32 v[132:133], v[18:19], v[34:35], v[132:133] op_sel_hi:[1,0,1]
	v_pk_fma_f32 v[94:95], v[18:19], v[126:127], v[94:95] op_sel_hi:[1,0,1]
	v_pk_fma_f32 v[132:133], v[14:15], v[34:35], v[132:133] op_sel:[0,1,0]
	v_pk_fma_f32 v[94:95], v[14:15], v[126:127], v[94:95] op_sel:[0,1,0]
	v_cvt_pk_f16_f32 v94, v94, v95
	v_add_f32_dpp v132, v132, v132 quad_perm:[1,0,3,2] row_mask:0xf bank_mask:0xf bound_ctrl:1
	v_add_f32_dpp v133, v133, v133 quad_perm:[1,0,3,2] row_mask:0xf bank_mask:0xf bound_ctrl:1
	ds_write_b32 v93, v94 offset:1024
	v_pk_fma_f32 v[16:17], v[28:29], v[90:91], v[16:17] op_sel_hi:[0,1,1]
	v_add_f32_dpp v132, v132, v132 quad_perm:[2,3,0,1] row_mask:0xf bank_mask:0xf bound_ctrl:1
	v_add_f32_dpp v133, v133, v133 quad_perm:[2,3,0,1] row_mask:0xf bank_mask:0xf bound_ctrl:1
	v_pk_fma_f32 v[12:13], v[28:29], v[90:91], v[12:13] op_sel:[1,0,0]
	v_add_f32_dpp v132, v132, v132 row_half_mirror row_mask:0xf bank_mask:0xf bound_ctrl:1
	v_add_f32_dpp v133, v133, v133 row_half_mirror row_mask:0xf bank_mask:0xf bound_ctrl:1
	v_pk_fma_f32 v[18:19], v[30:31], v[90:91], v[18:19] op_sel_hi:[0,1,1]
	v_pk_fma_f32 v[14:15], v[30:31], v[90:91], v[14:15] op_sel:[1,0,0]
	ds_read_b64 v[90:91], v115 offset:20992
	ds_read_b128 v[94:97], v42 offset:12800
	ds_read_b128 v[116:119], v42 offset:16896
	ds_read_b128 v[120:123], v42 offset:8704
	ds_read_b128 v[124:127], v42 offset:512
	ds_read_b64 v[130:131], v92 offset:256
	v_add_f32_dpp v132, v132, v132 row_mirror row_mask:0xf bank_mask:0xf bound_ctrl:1
	v_add_f32_dpp v133, v133, v133 row_mirror row_mask:0xf bank_mask:0xf bound_ctrl:1
	v_pk_fma_f32 v[16:17], v[24:25], v[132:133], v[16:17] op_sel_hi:[0,1,1]
	v_pk_fma_f32 v[12:13], v[24:25], v[132:133], v[12:13] op_sel:[1,0,0]
	v_pk_fma_f32 v[18:19], v[26:27], v[132:133], v[18:19] op_sel_hi:[0,1,1]
	v_pk_fma_f32 v[14:15], v[26:27], v[132:133], v[14:15] op_sel:[1,0,0]
	s_waitcnt lgkmcnt(4)
	v_pk_mul_f32 v[132:133], v[16:17], v[94:95] op_sel_hi:[1,0]
	v_pk_mul_f32 v[24:25], v[16:17], v[20:21] op_sel_hi:[1,0]
	v_pk_fma_f32 v[132:133], v[12:13], v[94:95], v[132:133] op_sel:[0,1,0]
	v_pk_fma_f32 v[24:25], v[12:13], v[20:21], v[24:25] op_sel:[0,1,0]
	v_pk_fma_f32 v[132:133], v[18:19], v[96:97], v[132:133] op_sel_hi:[1,0,1]
	v_pk_fma_f32 v[24:25], v[18:19], v[22:23], v[24:25] op_sel_hi:[1,0,1]
	v_pk_fma_f32 v[132:133], v[14:15], v[96:97], v[132:133] op_sel:[0,1,0]
	v_pk_fma_f32 v[24:25], v[14:15], v[22:23], v[24:25] op_sel:[0,1,0]
	v_cvt_pk_f16_f32 v24, v24, v25
	v_add_f32_dpp v132, v132, v132 quad_perm:[1,0,3,2] row_mask:0xf bank_mask:0xf bound_ctrl:1
	v_add_f32_dpp v133, v133, v133 quad_perm:[1,0,3,2] row_mask:0xf bank_mask:0xf bound_ctrl:1
	ds_write_b32 v93, v24 offset:2048
	ds_read_b128 v[32:35], v114 offset:13312
	ds_read_b128 v[24:27], v114 offset:17408
	ds_read_b128 v[28:31], v114 offset:9216
	ds_read_b128 v[20:23], v114 offset:1024
	s_waitcnt lgkmcnt(5)
	v_pk_fma_f32 v[16:17], v[120:121], v[130:131], v[16:17] op_sel_hi:[0,1,1]
	v_add_f32_dpp v132, v132, v132 quad_perm:[2,3,0,1] row_mask:0xf bank_mask:0xf bound_ctrl:1
	v_add_f32_dpp v133, v133, v133 quad_perm:[2,3,0,1] row_mask:0xf bank_mask:0xf bound_ctrl:1
	v_pk_fma_f32 v[12:13], v[120:121], v[130:131], v[12:13] op_sel:[1,0,0]
	v_add_f32_dpp v132, v132, v132 row_half_mirror row_mask:0xf bank_mask:0xf bound_ctrl:1
	v_add_f32_dpp v133, v133, v133 row_half_mirror row_mask:0xf bank_mask:0xf bound_ctrl:1
	v_pk_fma_f32 v[18:19], v[122:123], v[130:131], v[18:19] op_sel_hi:[0,1,1]
	v_pk_fma_f32 v[14:15], v[122:123], v[130:131], v[14:15] op_sel:[1,0,0]
	v_add_f32_dpp v132, v132, v132 row_mirror row_mask:0xf bank_mask:0xf bound_ctrl:1
	v_add_f32_dpp v133, v133, v133 row_mirror row_mask:0xf bank_mask:0xf bound_ctrl:1
	v_pk_fma_f32 v[16:17], v[116:117], v[132:133], v[16:17] op_sel_hi:[0,1,1]
	v_pk_fma_f32 v[12:13], v[116:117], v[132:133], v[12:13] op_sel:[1,0,0]
	v_pk_fma_f32 v[18:19], v[118:119], v[132:133], v[18:19] op_sel_hi:[0,1,1]
	v_pk_fma_f32 v[14:15], v[118:119], v[132:133], v[14:15] op_sel:[1,0,0]
	s_waitcnt lgkmcnt(0)
	v_pk_mul_f32 v[132:133], v[16:17], v[32:33] op_sel_hi:[1,0]
	v_pk_mul_f32 v[94:95], v[16:17], v[124:125] op_sel_hi:[1,0]
	v_pk_fma_f32 v[132:133], v[12:13], v[32:33], v[132:133] op_sel:[0,1,0]
	v_pk_fma_f32 v[94:95], v[12:13], v[124:125], v[94:95] op_sel:[0,1,0]
	v_pk_fma_f32 v[132:133], v[18:19], v[34:35], v[132:133] op_sel_hi:[1,0,1]
	v_pk_fma_f32 v[94:95], v[18:19], v[126:127], v[94:95] op_sel_hi:[1,0,1]
	v_pk_fma_f32 v[132:133], v[14:15], v[34:35], v[132:133] op_sel:[0,1,0]
	v_pk_fma_f32 v[94:95], v[14:15], v[126:127], v[94:95] op_sel:[0,1,0]
	v_cvt_pk_f16_f32 v94, v94, v95
	v_add_f32_dpp v132, v132, v132 quad_perm:[1,0,3,2] row_mask:0xf bank_mask:0xf bound_ctrl:1
	v_add_f32_dpp v133, v133, v133 quad_perm:[1,0,3,2] row_mask:0xf bank_mask:0xf bound_ctrl:1
	ds_write_b32 v93, v94 offset:3072
	v_pk_fma_f32 v[16:17], v[28:29], v[90:91], v[16:17] op_sel_hi:[0,1,1]
	v_add_f32_dpp v132, v132, v132 quad_perm:[2,3,0,1] row_mask:0xf bank_mask:0xf bound_ctrl:1
	v_add_f32_dpp v133, v133, v133 quad_perm:[2,3,0,1] row_mask:0xf bank_mask:0xf bound_ctrl:1
	v_pk_fma_f32 v[12:13], v[28:29], v[90:91], v[12:13] op_sel:[1,0,0]
	v_add_f32_dpp v132, v132, v132 row_half_mirror row_mask:0xf bank_mask:0xf bound_ctrl:1
	v_add_f32_dpp v133, v133, v133 row_half_mirror row_mask:0xf bank_mask:0xf bound_ctrl:1
	v_pk_fma_f32 v[18:19], v[30:31], v[90:91], v[18:19] op_sel_hi:[0,1,1]
	v_pk_fma_f32 v[14:15], v[30:31], v[90:91], v[14:15] op_sel:[1,0,0]
	ds_read_b64 v[90:91], v115 offset:21248
	ds_read_b128 v[94:97], v42 offset:13312
	ds_read_b128 v[116:119], v42 offset:17408
	ds_read_b128 v[120:123], v42 offset:9216
	ds_read_b128 v[124:127], v42 offset:1024
	ds_read_b64 v[130:131], v92 offset:512
	v_add_f32_dpp v132, v132, v132 row_mirror row_mask:0xf bank_mask:0xf bound_ctrl:1
	v_add_f32_dpp v133, v133, v133 row_mirror row_mask:0xf bank_mask:0xf bound_ctrl:1
	v_pk_fma_f32 v[16:17], v[24:25], v[132:133], v[16:17] op_sel_hi:[0,1,1]
	v_pk_fma_f32 v[12:13], v[24:25], v[132:133], v[12:13] op_sel:[1,0,0]
	v_pk_fma_f32 v[18:19], v[26:27], v[132:133], v[18:19] op_sel_hi:[0,1,1]
	v_pk_fma_f32 v[14:15], v[26:27], v[132:133], v[14:15] op_sel:[1,0,0]
	s_waitcnt lgkmcnt(4)
	v_pk_mul_f32 v[132:133], v[16:17], v[94:95] op_sel_hi:[1,0]
	v_pk_mul_f32 v[24:25], v[16:17], v[20:21] op_sel_hi:[1,0]
	v_pk_fma_f32 v[132:133], v[12:13], v[94:95], v[132:133] op_sel:[0,1,0]
	v_pk_fma_f32 v[24:25], v[12:13], v[20:21], v[24:25] op_sel:[0,1,0]
	v_pk_fma_f32 v[132:133], v[18:19], v[96:97], v[132:133] op_sel_hi:[1,0,1]
	v_pk_fma_f32 v[24:25], v[18:19], v[22:23], v[24:25] op_sel_hi:[1,0,1]
	v_pk_fma_f32 v[132:133], v[14:15], v[96:97], v[132:133] op_sel:[0,1,0]
	v_pk_fma_f32 v[24:25], v[14:15], v[22:23], v[24:25] op_sel:[0,1,0]
	v_cvt_pk_f16_f32 v24, v24, v25
	v_add_f32_dpp v132, v132, v132 quad_perm:[1,0,3,2] row_mask:0xf bank_mask:0xf bound_ctrl:1
	v_add_f32_dpp v133, v133, v133 quad_perm:[1,0,3,2] row_mask:0xf bank_mask:0xf bound_ctrl:1
	ds_write_b32 v93, v24 offset:4096
	ds_read_b128 v[32:35], v114 offset:13824
	ds_read_b128 v[24:27], v114 offset:17920
	ds_read_b128 v[28:31], v114 offset:9728
	ds_read_b128 v[20:23], v114 offset:1536
	s_waitcnt lgkmcnt(5)
	v_pk_fma_f32 v[16:17], v[120:121], v[130:131], v[16:17] op_sel_hi:[0,1,1]
	v_add_f32_dpp v132, v132, v132 quad_perm:[2,3,0,1] row_mask:0xf bank_mask:0xf bound_ctrl:1
	v_add_f32_dpp v133, v133, v133 quad_perm:[2,3,0,1] row_mask:0xf bank_mask:0xf bound_ctrl:1
	v_pk_fma_f32 v[12:13], v[120:121], v[130:131], v[12:13] op_sel:[1,0,0]
	v_add_f32_dpp v132, v132, v132 row_half_mirror row_mask:0xf bank_mask:0xf bound_ctrl:1
	v_add_f32_dpp v133, v133, v133 row_half_mirror row_mask:0xf bank_mask:0xf bound_ctrl:1
	v_pk_fma_f32 v[18:19], v[122:123], v[130:131], v[18:19] op_sel_hi:[0,1,1]
	v_pk_fma_f32 v[14:15], v[122:123], v[130:131], v[14:15] op_sel:[1,0,0]
	v_add_f32_dpp v132, v132, v132 row_mirror row_mask:0xf bank_mask:0xf bound_ctrl:1
	v_add_f32_dpp v133, v133, v133 row_mirror row_mask:0xf bank_mask:0xf bound_ctrl:1
	v_pk_fma_f32 v[16:17], v[116:117], v[132:133], v[16:17] op_sel_hi:[0,1,1]
	v_pk_fma_f32 v[12:13], v[116:117], v[132:133], v[12:13] op_sel:[1,0,0]
	v_pk_fma_f32 v[18:19], v[118:119], v[132:133], v[18:19] op_sel_hi:[0,1,1]
	v_pk_fma_f32 v[14:15], v[118:119], v[132:133], v[14:15] op_sel:[1,0,0]
	s_waitcnt lgkmcnt(0)
	v_pk_mul_f32 v[132:133], v[16:17], v[32:33] op_sel_hi:[1,0]
	v_pk_mul_f32 v[94:95], v[16:17], v[124:125] op_sel_hi:[1,0]
	v_pk_fma_f32 v[132:133], v[12:13], v[32:33], v[132:133] op_sel:[0,1,0]
	v_pk_fma_f32 v[94:95], v[12:13], v[124:125], v[94:95] op_sel:[0,1,0]
	v_pk_fma_f32 v[132:133], v[18:19], v[34:35], v[132:133] op_sel_hi:[1,0,1]
	v_pk_fma_f32 v[94:95], v[18:19], v[126:127], v[94:95] op_sel_hi:[1,0,1]
	v_pk_fma_f32 v[132:133], v[14:15], v[34:35], v[132:133] op_sel:[0,1,0]
	v_pk_fma_f32 v[94:95], v[14:15], v[126:127], v[94:95] op_sel:[0,1,0]
	v_cvt_pk_f16_f32 v94, v94, v95
	v_add_f32_dpp v132, v132, v132 quad_perm:[1,0,3,2] row_mask:0xf bank_mask:0xf bound_ctrl:1
	v_add_f32_dpp v133, v133, v133 quad_perm:[1,0,3,2] row_mask:0xf bank_mask:0xf bound_ctrl:1
	ds_write_b32 v93, v94 offset:5120
	v_pk_fma_f32 v[16:17], v[28:29], v[90:91], v[16:17] op_sel_hi:[0,1,1]
	v_add_f32_dpp v132, v132, v132 quad_perm:[2,3,0,1] row_mask:0xf bank_mask:0xf bound_ctrl:1
	v_add_f32_dpp v133, v133, v133 quad_perm:[2,3,0,1] row_mask:0xf bank_mask:0xf bound_ctrl:1
	v_pk_fma_f32 v[12:13], v[28:29], v[90:91], v[12:13] op_sel:[1,0,0]
	v_add_f32_dpp v132, v132, v132 row_half_mirror row_mask:0xf bank_mask:0xf bound_ctrl:1
	v_add_f32_dpp v133, v133, v133 row_half_mirror row_mask:0xf bank_mask:0xf bound_ctrl:1
	v_pk_fma_f32 v[18:19], v[30:31], v[90:91], v[18:19] op_sel_hi:[0,1,1]
	v_pk_fma_f32 v[14:15], v[30:31], v[90:91], v[14:15] op_sel:[1,0,0]
	ds_read_b64 v[90:91], v115 offset:21504
	ds_read_b128 v[94:97], v42 offset:13824
	ds_read_b128 v[116:119], v42 offset:17920
	ds_read_b128 v[120:123], v42 offset:9728
	ds_read_b128 v[124:127], v42 offset:1536
	ds_read_b64 v[130:131], v92 offset:768
	v_add_f32_dpp v132, v132, v132 row_mirror row_mask:0xf bank_mask:0xf bound_ctrl:1
	v_add_f32_dpp v133, v133, v133 row_mirror row_mask:0xf bank_mask:0xf bound_ctrl:1
	v_pk_fma_f32 v[16:17], v[24:25], v[132:133], v[16:17] op_sel_hi:[0,1,1]
	v_pk_fma_f32 v[12:13], v[24:25], v[132:133], v[12:13] op_sel:[1,0,0]
	v_pk_fma_f32 v[18:19], v[26:27], v[132:133], v[18:19] op_sel_hi:[0,1,1]
	v_pk_fma_f32 v[14:15], v[26:27], v[132:133], v[14:15] op_sel:[1,0,0]
	s_waitcnt lgkmcnt(4)
	v_pk_mul_f32 v[132:133], v[16:17], v[94:95] op_sel_hi:[1,0]
	v_pk_mul_f32 v[24:25], v[16:17], v[20:21] op_sel_hi:[1,0]
	v_pk_fma_f32 v[132:133], v[12:13], v[94:95], v[132:133] op_sel:[0,1,0]
	v_pk_fma_f32 v[24:25], v[12:13], v[20:21], v[24:25] op_sel:[0,1,0]
	v_pk_fma_f32 v[132:133], v[18:19], v[96:97], v[132:133] op_sel_hi:[1,0,1]
	v_pk_fma_f32 v[24:25], v[18:19], v[22:23], v[24:25] op_sel_hi:[1,0,1]
	v_pk_fma_f32 v[132:133], v[14:15], v[96:97], v[132:133] op_sel:[0,1,0]
	v_pk_fma_f32 v[24:25], v[14:15], v[22:23], v[24:25] op_sel:[0,1,0]
	v_cvt_pk_f16_f32 v24, v24, v25
	v_add_f32_dpp v132, v132, v132 quad_perm:[1,0,3,2] row_mask:0xf bank_mask:0xf bound_ctrl:1
	v_add_f32_dpp v133, v133, v133 quad_perm:[1,0,3,2] row_mask:0xf bank_mask:0xf bound_ctrl:1
	ds_write_b32 v93, v24 offset:6144
	ds_read_b128 v[32:35], v114 offset:14336
	ds_read_b128 v[24:27], v114 offset:18432
	ds_read_b128 v[28:31], v114 offset:10240
	ds_read_b128 v[20:23], v114 offset:2048
	s_waitcnt lgkmcnt(5)
	v_pk_fma_f32 v[16:17], v[120:121], v[130:131], v[16:17] op_sel_hi:[0,1,1]
	v_add_f32_dpp v132, v132, v132 quad_perm:[2,3,0,1] row_mask:0xf bank_mask:0xf bound_ctrl:1
	v_add_f32_dpp v133, v133, v133 quad_perm:[2,3,0,1] row_mask:0xf bank_mask:0xf bound_ctrl:1
	v_pk_fma_f32 v[12:13], v[120:121], v[130:131], v[12:13] op_sel:[1,0,0]
	v_add_f32_dpp v132, v132, v132 row_half_mirror row_mask:0xf bank_mask:0xf bound_ctrl:1
	v_add_f32_dpp v133, v133, v133 row_half_mirror row_mask:0xf bank_mask:0xf bound_ctrl:1
	v_pk_fma_f32 v[18:19], v[122:123], v[130:131], v[18:19] op_sel_hi:[0,1,1]
	v_pk_fma_f32 v[14:15], v[122:123], v[130:131], v[14:15] op_sel:[1,0,0]
	v_add_f32_dpp v132, v132, v132 row_mirror row_mask:0xf bank_mask:0xf bound_ctrl:1
	v_add_f32_dpp v133, v133, v133 row_mirror row_mask:0xf bank_mask:0xf bound_ctrl:1
	v_pk_fma_f32 v[16:17], v[116:117], v[132:133], v[16:17] op_sel_hi:[0,1,1]
	v_pk_fma_f32 v[12:13], v[116:117], v[132:133], v[12:13] op_sel:[1,0,0]
	v_pk_fma_f32 v[18:19], v[118:119], v[132:133], v[18:19] op_sel_hi:[0,1,1]
	v_pk_fma_f32 v[14:15], v[118:119], v[132:133], v[14:15] op_sel:[1,0,0]
	s_waitcnt lgkmcnt(0)
	v_pk_mul_f32 v[132:133], v[16:17], v[32:33] op_sel_hi:[1,0]
	v_pk_mul_f32 v[94:95], v[16:17], v[124:125] op_sel_hi:[1,0]
	v_pk_fma_f32 v[132:133], v[12:13], v[32:33], v[132:133] op_sel:[0,1,0]
	v_pk_fma_f32 v[94:95], v[12:13], v[124:125], v[94:95] op_sel:[0,1,0]
	v_pk_fma_f32 v[132:133], v[18:19], v[34:35], v[132:133] op_sel_hi:[1,0,1]
	v_pk_fma_f32 v[94:95], v[18:19], v[126:127], v[94:95] op_sel_hi:[1,0,1]
	v_pk_fma_f32 v[132:133], v[14:15], v[34:35], v[132:133] op_sel:[0,1,0]
	v_pk_fma_f32 v[94:95], v[14:15], v[126:127], v[94:95] op_sel:[0,1,0]
	v_cvt_pk_f16_f32 v94, v94, v95
	v_add_f32_dpp v132, v132, v132 quad_perm:[1,0,3,2] row_mask:0xf bank_mask:0xf bound_ctrl:1
	v_add_f32_dpp v133, v133, v133 quad_perm:[1,0,3,2] row_mask:0xf bank_mask:0xf bound_ctrl:1
	ds_write_b32 v93, v94 offset:7168
	v_pk_fma_f32 v[16:17], v[28:29], v[90:91], v[16:17] op_sel_hi:[0,1,1]
	v_add_f32_dpp v132, v132, v132 quad_perm:[2,3,0,1] row_mask:0xf bank_mask:0xf bound_ctrl:1
	v_add_f32_dpp v133, v133, v133 quad_perm:[2,3,0,1] row_mask:0xf bank_mask:0xf bound_ctrl:1
	v_pk_fma_f32 v[12:13], v[28:29], v[90:91], v[12:13] op_sel:[1,0,0]
	v_add_f32_dpp v132, v132, v132 row_half_mirror row_mask:0xf bank_mask:0xf bound_ctrl:1
	v_add_f32_dpp v133, v133, v133 row_half_mirror row_mask:0xf bank_mask:0xf bound_ctrl:1
	v_pk_fma_f32 v[18:19], v[30:31], v[90:91], v[18:19] op_sel_hi:[0,1,1]
	v_pk_fma_f32 v[14:15], v[30:31], v[90:91], v[14:15] op_sel:[1,0,0]
	ds_read_b64 v[90:91], v115 offset:21760
	ds_read_b128 v[94:97], v42 offset:14336
	ds_read_b128 v[116:119], v42 offset:18432
	ds_read_b128 v[120:123], v42 offset:10240
	ds_read_b128 v[124:127], v42 offset:2048
	ds_read_b64 v[130:131], v92 offset:1024
	v_add_f32_dpp v132, v132, v132 row_mirror row_mask:0xf bank_mask:0xf bound_ctrl:1
	v_add_f32_dpp v133, v133, v133 row_mirror row_mask:0xf bank_mask:0xf bound_ctrl:1
	v_pk_fma_f32 v[16:17], v[24:25], v[132:133], v[16:17] op_sel_hi:[0,1,1]
	v_pk_fma_f32 v[12:13], v[24:25], v[132:133], v[12:13] op_sel:[1,0,0]
	v_pk_fma_f32 v[18:19], v[26:27], v[132:133], v[18:19] op_sel_hi:[0,1,1]
	v_pk_fma_f32 v[14:15], v[26:27], v[132:133], v[14:15] op_sel:[1,0,0]
	s_waitcnt lgkmcnt(4)
	v_pk_mul_f32 v[132:133], v[16:17], v[94:95] op_sel_hi:[1,0]
	v_pk_mul_f32 v[24:25], v[16:17], v[20:21] op_sel_hi:[1,0]
	v_pk_fma_f32 v[132:133], v[12:13], v[94:95], v[132:133] op_sel:[0,1,0]
	v_pk_fma_f32 v[24:25], v[12:13], v[20:21], v[24:25] op_sel:[0,1,0]
	v_pk_fma_f32 v[132:133], v[18:19], v[96:97], v[132:133] op_sel_hi:[1,0,1]
	v_pk_fma_f32 v[24:25], v[18:19], v[22:23], v[24:25] op_sel_hi:[1,0,1]
	v_pk_fma_f32 v[132:133], v[14:15], v[96:97], v[132:133] op_sel:[0,1,0]
	v_pk_fma_f32 v[24:25], v[14:15], v[22:23], v[24:25] op_sel:[0,1,0]
	v_cvt_pk_f16_f32 v24, v24, v25
	v_add_f32_dpp v132, v132, v132 quad_perm:[1,0,3,2] row_mask:0xf bank_mask:0xf bound_ctrl:1
	v_add_f32_dpp v133, v133, v133 quad_perm:[1,0,3,2] row_mask:0xf bank_mask:0xf bound_ctrl:1
	ds_write_b32 v93, v24 offset:8192
	ds_read_b128 v[32:35], v114 offset:14848
	ds_read_b128 v[24:27], v114 offset:18944
	ds_read_b128 v[28:31], v114 offset:10752
	ds_read_b128 v[20:23], v114 offset:2560
	s_waitcnt lgkmcnt(5)
	v_pk_fma_f32 v[16:17], v[120:121], v[130:131], v[16:17] op_sel_hi:[0,1,1]
	v_add_f32_dpp v132, v132, v132 quad_perm:[2,3,0,1] row_mask:0xf bank_mask:0xf bound_ctrl:1
	v_add_f32_dpp v133, v133, v133 quad_perm:[2,3,0,1] row_mask:0xf bank_mask:0xf bound_ctrl:1
	v_pk_fma_f32 v[12:13], v[120:121], v[130:131], v[12:13] op_sel:[1,0,0]
	v_add_f32_dpp v132, v132, v132 row_half_mirror row_mask:0xf bank_mask:0xf bound_ctrl:1
	v_add_f32_dpp v133, v133, v133 row_half_mirror row_mask:0xf bank_mask:0xf bound_ctrl:1
	v_pk_fma_f32 v[18:19], v[122:123], v[130:131], v[18:19] op_sel_hi:[0,1,1]
	v_pk_fma_f32 v[14:15], v[122:123], v[130:131], v[14:15] op_sel:[1,0,0]
	v_add_f32_dpp v132, v132, v132 row_mirror row_mask:0xf bank_mask:0xf bound_ctrl:1
	v_add_f32_dpp v133, v133, v133 row_mirror row_mask:0xf bank_mask:0xf bound_ctrl:1
	v_pk_fma_f32 v[16:17], v[116:117], v[132:133], v[16:17] op_sel_hi:[0,1,1]
	v_pk_fma_f32 v[12:13], v[116:117], v[132:133], v[12:13] op_sel:[1,0,0]
	v_pk_fma_f32 v[18:19], v[118:119], v[132:133], v[18:19] op_sel_hi:[0,1,1]
	v_pk_fma_f32 v[14:15], v[118:119], v[132:133], v[14:15] op_sel:[1,0,0]
	s_waitcnt lgkmcnt(0)
	v_pk_mul_f32 v[132:133], v[16:17], v[32:33] op_sel_hi:[1,0]
	v_pk_mul_f32 v[94:95], v[16:17], v[124:125] op_sel_hi:[1,0]
	v_pk_fma_f32 v[132:133], v[12:13], v[32:33], v[132:133] op_sel:[0,1,0]
	v_pk_fma_f32 v[94:95], v[12:13], v[124:125], v[94:95] op_sel:[0,1,0]
	v_pk_fma_f32 v[132:133], v[18:19], v[34:35], v[132:133] op_sel_hi:[1,0,1]
	v_pk_fma_f32 v[94:95], v[18:19], v[126:127], v[94:95] op_sel_hi:[1,0,1]
	v_pk_fma_f32 v[132:133], v[14:15], v[34:35], v[132:133] op_sel:[0,1,0]
	v_pk_fma_f32 v[94:95], v[14:15], v[126:127], v[94:95] op_sel:[0,1,0]
	v_cvt_pk_f16_f32 v94, v94, v95
	v_add_f32_dpp v132, v132, v132 quad_perm:[1,0,3,2] row_mask:0xf bank_mask:0xf bound_ctrl:1
	v_add_f32_dpp v133, v133, v133 quad_perm:[1,0,3,2] row_mask:0xf bank_mask:0xf bound_ctrl:1
	ds_write_b32 v93, v94 offset:9216
	v_pk_fma_f32 v[16:17], v[28:29], v[90:91], v[16:17] op_sel_hi:[0,1,1]
	v_add_f32_dpp v132, v132, v132 quad_perm:[2,3,0,1] row_mask:0xf bank_mask:0xf bound_ctrl:1
	v_add_f32_dpp v133, v133, v133 quad_perm:[2,3,0,1] row_mask:0xf bank_mask:0xf bound_ctrl:1
	v_pk_fma_f32 v[12:13], v[28:29], v[90:91], v[12:13] op_sel:[1,0,0]
	v_add_f32_dpp v132, v132, v132 row_half_mirror row_mask:0xf bank_mask:0xf bound_ctrl:1
	v_add_f32_dpp v133, v133, v133 row_half_mirror row_mask:0xf bank_mask:0xf bound_ctrl:1
	v_pk_fma_f32 v[18:19], v[30:31], v[90:91], v[18:19] op_sel_hi:[0,1,1]
	v_pk_fma_f32 v[14:15], v[30:31], v[90:91], v[14:15] op_sel:[1,0,0]
	ds_read_b64 v[90:91], v115 offset:22016
	ds_read_b128 v[94:97], v42 offset:14848
	ds_read_b128 v[116:119], v42 offset:18944
	ds_read_b128 v[120:123], v42 offset:10752
	ds_read_b128 v[124:127], v42 offset:2560
	ds_read_b64 v[130:131], v92 offset:1280
	v_add_f32_dpp v132, v132, v132 row_mirror row_mask:0xf bank_mask:0xf bound_ctrl:1
	v_add_f32_dpp v133, v133, v133 row_mirror row_mask:0xf bank_mask:0xf bound_ctrl:1
	v_pk_fma_f32 v[16:17], v[24:25], v[132:133], v[16:17] op_sel_hi:[0,1,1]
	v_pk_fma_f32 v[12:13], v[24:25], v[132:133], v[12:13] op_sel:[1,0,0]
	v_pk_fma_f32 v[18:19], v[26:27], v[132:133], v[18:19] op_sel_hi:[0,1,1]
	v_pk_fma_f32 v[14:15], v[26:27], v[132:133], v[14:15] op_sel:[1,0,0]
	s_waitcnt lgkmcnt(4)
	v_pk_mul_f32 v[132:133], v[16:17], v[94:95] op_sel_hi:[1,0]
	v_pk_mul_f32 v[24:25], v[16:17], v[20:21] op_sel_hi:[1,0]
	v_pk_fma_f32 v[132:133], v[12:13], v[94:95], v[132:133] op_sel:[0,1,0]
	v_pk_fma_f32 v[24:25], v[12:13], v[20:21], v[24:25] op_sel:[0,1,0]
	v_pk_fma_f32 v[132:133], v[18:19], v[96:97], v[132:133] op_sel_hi:[1,0,1]
	v_pk_fma_f32 v[24:25], v[18:19], v[22:23], v[24:25] op_sel_hi:[1,0,1]
	v_pk_fma_f32 v[132:133], v[14:15], v[96:97], v[132:133] op_sel:[0,1,0]
	v_pk_fma_f32 v[24:25], v[14:15], v[22:23], v[24:25] op_sel:[0,1,0]
	v_cvt_pk_f16_f32 v24, v24, v25
	v_add_f32_dpp v132, v132, v132 quad_perm:[1,0,3,2] row_mask:0xf bank_mask:0xf bound_ctrl:1
	v_add_f32_dpp v133, v133, v133 quad_perm:[1,0,3,2] row_mask:0xf bank_mask:0xf bound_ctrl:1
	ds_write_b32 v93, v24 offset:10240
	ds_read_b128 v[32:35], v114 offset:15360
	ds_read_b128 v[24:27], v114 offset:19456
	ds_read_b128 v[28:31], v114 offset:11264
	ds_read_b128 v[20:23], v114 offset:3072
	s_waitcnt lgkmcnt(5)
	v_pk_fma_f32 v[16:17], v[120:121], v[130:131], v[16:17] op_sel_hi:[0,1,1]
	v_add_f32_dpp v132, v132, v132 quad_perm:[2,3,0,1] row_mask:0xf bank_mask:0xf bound_ctrl:1
	v_add_f32_dpp v133, v133, v133 quad_perm:[2,3,0,1] row_mask:0xf bank_mask:0xf bound_ctrl:1
	v_pk_fma_f32 v[12:13], v[120:121], v[130:131], v[12:13] op_sel:[1,0,0]
	v_add_f32_dpp v132, v132, v132 row_half_mirror row_mask:0xf bank_mask:0xf bound_ctrl:1
	v_add_f32_dpp v133, v133, v133 row_half_mirror row_mask:0xf bank_mask:0xf bound_ctrl:1
	v_pk_fma_f32 v[18:19], v[122:123], v[130:131], v[18:19] op_sel_hi:[0,1,1]
	v_pk_fma_f32 v[14:15], v[122:123], v[130:131], v[14:15] op_sel:[1,0,0]
	v_add_f32_dpp v132, v132, v132 row_mirror row_mask:0xf bank_mask:0xf bound_ctrl:1
	v_add_f32_dpp v133, v133, v133 row_mirror row_mask:0xf bank_mask:0xf bound_ctrl:1
	v_pk_fma_f32 v[16:17], v[116:117], v[132:133], v[16:17] op_sel_hi:[0,1,1]
	v_pk_fma_f32 v[12:13], v[116:117], v[132:133], v[12:13] op_sel:[1,0,0]
	v_pk_fma_f32 v[18:19], v[118:119], v[132:133], v[18:19] op_sel_hi:[0,1,1]
	v_pk_fma_f32 v[14:15], v[118:119], v[132:133], v[14:15] op_sel:[1,0,0]
	s_waitcnt lgkmcnt(0)
	v_pk_mul_f32 v[132:133], v[16:17], v[32:33] op_sel_hi:[1,0]
	v_pk_mul_f32 v[94:95], v[16:17], v[124:125] op_sel_hi:[1,0]
	v_pk_fma_f32 v[132:133], v[12:13], v[32:33], v[132:133] op_sel:[0,1,0]
	v_pk_fma_f32 v[94:95], v[12:13], v[124:125], v[94:95] op_sel:[0,1,0]
	v_pk_fma_f32 v[132:133], v[18:19], v[34:35], v[132:133] op_sel_hi:[1,0,1]
	v_pk_fma_f32 v[94:95], v[18:19], v[126:127], v[94:95] op_sel_hi:[1,0,1]
	v_pk_fma_f32 v[132:133], v[14:15], v[34:35], v[132:133] op_sel:[0,1,0]
	v_pk_fma_f32 v[94:95], v[14:15], v[126:127], v[94:95] op_sel:[0,1,0]
	v_cvt_pk_f16_f32 v94, v94, v95
	v_add_f32_dpp v132, v132, v132 quad_perm:[1,0,3,2] row_mask:0xf bank_mask:0xf bound_ctrl:1
	v_add_f32_dpp v133, v133, v133 quad_perm:[1,0,3,2] row_mask:0xf bank_mask:0xf bound_ctrl:1
	ds_write_b32 v93, v94 offset:11264
	v_pk_fma_f32 v[16:17], v[28:29], v[90:91], v[16:17] op_sel_hi:[0,1,1]
	v_add_f32_dpp v132, v132, v132 quad_perm:[2,3,0,1] row_mask:0xf bank_mask:0xf bound_ctrl:1
	v_add_f32_dpp v133, v133, v133 quad_perm:[2,3,0,1] row_mask:0xf bank_mask:0xf bound_ctrl:1
	v_pk_fma_f32 v[12:13], v[28:29], v[90:91], v[12:13] op_sel:[1,0,0]
	v_add_f32_dpp v132, v132, v132 row_half_mirror row_mask:0xf bank_mask:0xf bound_ctrl:1
	v_add_f32_dpp v133, v133, v133 row_half_mirror row_mask:0xf bank_mask:0xf bound_ctrl:1
	v_pk_fma_f32 v[18:19], v[30:31], v[90:91], v[18:19] op_sel_hi:[0,1,1]
	v_pk_fma_f32 v[14:15], v[30:31], v[90:91], v[14:15] op_sel:[1,0,0]
	ds_read_b64 v[90:91], v115 offset:22272
	ds_read_b128 v[94:97], v42 offset:15360
	ds_read_b128 v[116:119], v42 offset:19456
	ds_read_b128 v[120:123], v42 offset:11264
	ds_read_b128 v[124:127], v42 offset:3072
	ds_read_b64 v[130:131], v92 offset:1536
	v_add_f32_dpp v132, v132, v132 row_mirror row_mask:0xf bank_mask:0xf bound_ctrl:1
	v_add_f32_dpp v133, v133, v133 row_mirror row_mask:0xf bank_mask:0xf bound_ctrl:1
	v_pk_fma_f32 v[16:17], v[24:25], v[132:133], v[16:17] op_sel_hi:[0,1,1]
	v_pk_fma_f32 v[12:13], v[24:25], v[132:133], v[12:13] op_sel:[1,0,0]
	v_pk_fma_f32 v[18:19], v[26:27], v[132:133], v[18:19] op_sel_hi:[0,1,1]
	v_pk_fma_f32 v[14:15], v[26:27], v[132:133], v[14:15] op_sel:[1,0,0]
	s_waitcnt lgkmcnt(4)
	v_pk_mul_f32 v[132:133], v[16:17], v[94:95] op_sel_hi:[1,0]
	v_pk_mul_f32 v[24:25], v[16:17], v[20:21] op_sel_hi:[1,0]
	v_pk_fma_f32 v[132:133], v[12:13], v[94:95], v[132:133] op_sel:[0,1,0]
	v_pk_fma_f32 v[24:25], v[12:13], v[20:21], v[24:25] op_sel:[0,1,0]
	v_pk_fma_f32 v[132:133], v[18:19], v[96:97], v[132:133] op_sel_hi:[1,0,1]
	v_pk_fma_f32 v[24:25], v[18:19], v[22:23], v[24:25] op_sel_hi:[1,0,1]
	v_pk_fma_f32 v[132:133], v[14:15], v[96:97], v[132:133] op_sel:[0,1,0]
	v_pk_fma_f32 v[24:25], v[14:15], v[22:23], v[24:25] op_sel:[0,1,0]
	v_cvt_pk_f16_f32 v24, v24, v25
	v_add_f32_dpp v132, v132, v132 quad_perm:[1,0,3,2] row_mask:0xf bank_mask:0xf bound_ctrl:1
	v_add_f32_dpp v133, v133, v133 quad_perm:[1,0,3,2] row_mask:0xf bank_mask:0xf bound_ctrl:1
	ds_write_b32 v93, v24 offset:12288
	ds_read_b128 v[32:35], v114 offset:15872
	ds_read_b128 v[24:27], v114 offset:19968
	ds_read_b128 v[28:31], v114 offset:11776
	ds_read_b128 v[20:23], v114 offset:3584
	s_waitcnt lgkmcnt(5)
	v_pk_fma_f32 v[16:17], v[120:121], v[130:131], v[16:17] op_sel_hi:[0,1,1]
	v_add_f32_dpp v132, v132, v132 quad_perm:[2,3,0,1] row_mask:0xf bank_mask:0xf bound_ctrl:1
	v_add_f32_dpp v133, v133, v133 quad_perm:[2,3,0,1] row_mask:0xf bank_mask:0xf bound_ctrl:1
	v_pk_fma_f32 v[12:13], v[120:121], v[130:131], v[12:13] op_sel:[1,0,0]
	v_add_f32_dpp v132, v132, v132 row_half_mirror row_mask:0xf bank_mask:0xf bound_ctrl:1
	v_add_f32_dpp v133, v133, v133 row_half_mirror row_mask:0xf bank_mask:0xf bound_ctrl:1
	v_pk_fma_f32 v[18:19], v[122:123], v[130:131], v[18:19] op_sel_hi:[0,1,1]
	v_pk_fma_f32 v[14:15], v[122:123], v[130:131], v[14:15] op_sel:[1,0,0]
	v_add_f32_dpp v132, v132, v132 row_mirror row_mask:0xf bank_mask:0xf bound_ctrl:1
	v_add_f32_dpp v133, v133, v133 row_mirror row_mask:0xf bank_mask:0xf bound_ctrl:1
	v_pk_fma_f32 v[16:17], v[116:117], v[132:133], v[16:17] op_sel_hi:[0,1,1]
	v_pk_fma_f32 v[12:13], v[116:117], v[132:133], v[12:13] op_sel:[1,0,0]
	v_pk_fma_f32 v[18:19], v[118:119], v[132:133], v[18:19] op_sel_hi:[0,1,1]
	v_pk_fma_f32 v[14:15], v[118:119], v[132:133], v[14:15] op_sel:[1,0,0]
	s_waitcnt lgkmcnt(0)
	v_pk_mul_f32 v[132:133], v[16:17], v[32:33] op_sel_hi:[1,0]
	v_pk_mul_f32 v[94:95], v[16:17], v[124:125] op_sel_hi:[1,0]
	v_pk_fma_f32 v[132:133], v[12:13], v[32:33], v[132:133] op_sel:[0,1,0]
	v_pk_fma_f32 v[94:95], v[12:13], v[124:125], v[94:95] op_sel:[0,1,0]
	v_pk_fma_f32 v[132:133], v[18:19], v[34:35], v[132:133] op_sel_hi:[1,0,1]
	v_pk_fma_f32 v[94:95], v[18:19], v[126:127], v[94:95] op_sel_hi:[1,0,1]
	v_pk_fma_f32 v[132:133], v[14:15], v[34:35], v[132:133] op_sel:[0,1,0]
	v_pk_fma_f32 v[94:95], v[14:15], v[126:127], v[94:95] op_sel:[0,1,0]
	v_cvt_pk_f16_f32 v94, v94, v95
	v_add_f32_dpp v132, v132, v132 quad_perm:[1,0,3,2] row_mask:0xf bank_mask:0xf bound_ctrl:1
	v_add_f32_dpp v133, v133, v133 quad_perm:[1,0,3,2] row_mask:0xf bank_mask:0xf bound_ctrl:1
	ds_write_b32 v93, v94 offset:13312
	v_pk_fma_f32 v[16:17], v[28:29], v[90:91], v[16:17] op_sel_hi:[0,1,1]
	v_add_f32_dpp v132, v132, v132 quad_perm:[2,3,0,1] row_mask:0xf bank_mask:0xf bound_ctrl:1
	v_add_f32_dpp v133, v133, v133 quad_perm:[2,3,0,1] row_mask:0xf bank_mask:0xf bound_ctrl:1
	v_pk_fma_f32 v[12:13], v[28:29], v[90:91], v[12:13] op_sel:[1,0,0]
	v_add_f32_dpp v132, v132, v132 row_half_mirror row_mask:0xf bank_mask:0xf bound_ctrl:1
	v_add_f32_dpp v133, v133, v133 row_half_mirror row_mask:0xf bank_mask:0xf bound_ctrl:1
	v_pk_fma_f32 v[18:19], v[30:31], v[90:91], v[18:19] op_sel_hi:[0,1,1]
	v_pk_fma_f32 v[14:15], v[30:31], v[90:91], v[14:15] op_sel:[1,0,0]
	ds_read_b64 v[90:91], v115 offset:22272
	ds_read_b128 v[94:97], v42 offset:15872
	ds_read_b128 v[116:119], v42 offset:19968
	ds_read_b128 v[120:123], v42 offset:11776
	ds_read_b128 v[124:127], v42 offset:3584
	ds_read_b64 v[130:131], v92 offset:1792
	v_add_f32_dpp v132, v132, v132 row_mirror row_mask:0xf bank_mask:0xf bound_ctrl:1
	v_add_f32_dpp v133, v133, v133 row_mirror row_mask:0xf bank_mask:0xf bound_ctrl:1
	v_pk_fma_f32 v[16:17], v[24:25], v[132:133], v[16:17] op_sel_hi:[0,1,1]
	v_pk_fma_f32 v[12:13], v[24:25], v[132:133], v[12:13] op_sel:[1,0,0]
	v_pk_fma_f32 v[18:19], v[26:27], v[132:133], v[18:19] op_sel_hi:[0,1,1]
	v_pk_fma_f32 v[14:15], v[26:27], v[132:133], v[14:15] op_sel:[1,0,0]
	s_waitcnt lgkmcnt(4)
	v_pk_mul_f32 v[132:133], v[16:17], v[94:95] op_sel_hi:[1,0]
	v_pk_mul_f32 v[24:25], v[16:17], v[20:21] op_sel_hi:[1,0]
	v_pk_fma_f32 v[132:133], v[12:13], v[94:95], v[132:133] op_sel:[0,1,0]
	v_pk_fma_f32 v[24:25], v[12:13], v[20:21], v[24:25] op_sel:[0,1,0]
	v_pk_fma_f32 v[132:133], v[18:19], v[96:97], v[132:133] op_sel_hi:[1,0,1]
	v_pk_fma_f32 v[24:25], v[18:19], v[22:23], v[24:25] op_sel_hi:[1,0,1]
	v_pk_fma_f32 v[132:133], v[14:15], v[96:97], v[132:133] op_sel:[0,1,0]
	v_pk_fma_f32 v[24:25], v[14:15], v[22:23], v[24:25] op_sel:[0,1,0]
	v_cvt_pk_f16_f32 v24, v24, v25
	v_add_f32_dpp v132, v132, v132 quad_perm:[1,0,3,2] row_mask:0xf bank_mask:0xf bound_ctrl:1
	v_add_f32_dpp v133, v133, v133 quad_perm:[1,0,3,2] row_mask:0xf bank_mask:0xf bound_ctrl:1
	ds_write_b32 v93, v24 offset:14336
	ds_read_b128 v[32:35], v114 offset:15872
	ds_read_b128 v[24:27], v114 offset:19968
	ds_read_b128 v[28:31], v114 offset:11776
	ds_read_b128 v[20:23], v114 offset:3584
	s_waitcnt lgkmcnt(5)
	v_pk_fma_f32 v[16:17], v[120:121], v[130:131], v[16:17] op_sel_hi:[0,1,1]
	v_add_f32_dpp v132, v132, v132 quad_perm:[2,3,0,1] row_mask:0xf bank_mask:0xf bound_ctrl:1
	v_add_f32_dpp v133, v133, v133 quad_perm:[2,3,0,1] row_mask:0xf bank_mask:0xf bound_ctrl:1
	v_pk_fma_f32 v[12:13], v[120:121], v[130:131], v[12:13] op_sel:[1,0,0]
	v_add_f32_dpp v132, v132, v132 row_half_mirror row_mask:0xf bank_mask:0xf bound_ctrl:1
	v_add_f32_dpp v133, v133, v133 row_half_mirror row_mask:0xf bank_mask:0xf bound_ctrl:1
	v_pk_fma_f32 v[18:19], v[122:123], v[130:131], v[18:19] op_sel_hi:[0,1,1]
	v_pk_fma_f32 v[14:15], v[122:123], v[130:131], v[14:15] op_sel:[1,0,0]
	v_add_f32_dpp v132, v132, v132 row_mirror row_mask:0xf bank_mask:0xf bound_ctrl:1
	v_add_f32_dpp v133, v133, v133 row_mirror row_mask:0xf bank_mask:0xf bound_ctrl:1
	v_pk_fma_f32 v[16:17], v[116:117], v[132:133], v[16:17] op_sel_hi:[0,1,1]
	v_pk_fma_f32 v[12:13], v[116:117], v[132:133], v[12:13] op_sel:[1,0,0]
	v_pk_fma_f32 v[18:19], v[118:119], v[132:133], v[18:19] op_sel_hi:[0,1,1]
	v_pk_fma_f32 v[14:15], v[118:119], v[132:133], v[14:15] op_sel:[1,0,0]
	v_pk_mul_f32 v[94:95], v[16:17], v[124:125] op_sel_hi:[1,0]
	v_pk_fma_f32 v[94:95], v[12:13], v[124:125], v[94:95] op_sel:[0,1,0]
	v_pk_fma_f32 v[94:95], v[18:19], v[126:127], v[94:95] op_sel_hi:[1,0,1]
	v_pk_fma_f32 v[94:95], v[14:15], v[126:127], v[94:95] op_sel:[0,1,0]
	v_cvt_pk_f16_f32 v94, v94, v95
	ds_write_b32 v93, v94 offset:15360
	v_swap_b32 v17, v12
	v_swap_b32 v19, v14
	s_waitcnt vmcnt(10) lgkmcnt(1)
	v_cvt_f32_f16_sdwa v91, v60 dst_sel:DWORD dst_unused:UNUSED_PAD src0_sel:WORD_1
	v_cvt_f32_f16_e32 v90, v60
	v_cvt_f32_f16_sdwa v93, v61 dst_sel:DWORD dst_unused:UNUSED_PAD src0_sel:WORD_1
	v_cvt_f32_f16_e32 v92, v61
	s_waitcnt vmcnt(7)
	v_cvt_f32_f16_sdwa v25, v68 dst_sel:DWORD dst_unused:UNUSED_PAD src0_sel:WORD_1
	v_cvt_f32_f16_e32 v24, v68
	v_cvt_f32_f16_sdwa v27, v69 dst_sel:DWORD dst_unused:UNUSED_PAD src0_sel:WORD_1
	v_cvt_f32_f16_e32 v26, v69
	v_pk_mul_f32 v[30:31], v[0:1], v[90:91]
	v_pk_mul_f32 v[28:29], v[2:3], v[92:93]
	v_pk_mul_f32 v[96:97], v[30:31], v[30:31]
	v_pk_mul_f32 v[94:95], v[28:29], v[28:29]
	v_add_f32_e32 v42, v96, v97
	v_cvt_f32_f16_sdwa v33, v58 dst_sel:DWORD dst_unused:UNUSED_PAD src0_sel:WORD_1
	v_cvt_f32_f16_e32 v32, v58
	v_cvt_f32_f16_sdwa v35, v59 dst_sel:DWORD dst_unused:UNUSED_PAD src0_sel:WORD_1
	v_cvt_f32_f16_e32 v34, v59
	v_add_f32_e32 v42, v94, v42
	v_add_f32_e32 v42, v95, v42
	v_pk_add_f32 v[94:95], v[24:25], -1.0 op_sel_hi:[1,0]
	v_pk_add_f32 v[96:97], v[26:27], -1.0 op_sel_hi:[1,0]
	v_pk_fma_f32 v[94:95], v[4:5], v[94:95], 1.0 op_sel_hi:[1,1,0]
	v_pk_fma_f32 v[96:97], v[6:7], v[96:97], 1.0 op_sel_hi:[1,1,0]
	v_pk_mul_f32 v[94:95], v[90:91], v[94:95]
	v_pk_mul_f32 v[96:97], v[92:93], v[96:97]
	v_pk_mul_f32 v[90:91], v[32:33], v[94:95]
	v_pk_mul_f32 v[92:93], v[34:35], v[96:97]
	v_pk_mul_f32 v[90:91], v[8:9], v[90:91]
	v_pk_mul_f32 v[92:93], v[10:11], v[92:93]
	v_add_f32_e32 v90, v90, v91
	v_add_f32_e32 v91, v92, v93
	ds_read_b128 v[20:23], v114 offset:7936
	v_add_f32_e32 v90, v90, v91
	v_add_f32_dpp v42, v42, v42 quad_perm:[1,0,3,2] row_mask:0xf bank_mask:0xf bound_ctrl:1
	s_nop 0
	v_add_f32_dpp v90, v90, v90 quad_perm:[1,0,3,2] row_mask:0xf bank_mask:0xf bound_ctrl:1
	v_add_f32_dpp v42, v42, v42 quad_perm:[2,3,0,1] row_mask:0xf bank_mask:0xf bound_ctrl:1
	s_nop 0
	v_add_f32_dpp v90, v90, v90 quad_perm:[2,3,0,1] row_mask:0xf bank_mask:0xf bound_ctrl:1
	v_add_f32_dpp v42, v42, v42 row_half_mirror row_mask:0xf bank_mask:0xf bound_ctrl:1
	s_nop 0
	v_add_f32_dpp v90, v90, v90 row_half_mirror row_mask:0xf bank_mask:0xf bound_ctrl:1
	v_mov_b32_dpp v116, v42 row_mirror row_mask:0xf bank_mask:0xf bound_ctrl:1
	s_nop 0
	v_mov_b32_dpp v91, v90 row_mirror row_mask:0xf bank_mask:0xf bound_ctrl:1
	s_and_saveexec_b64 s[12:13], s[6:7]
	s_cbranch_execz .LBB0_419
	s_add_i32 s50, s94, 16
	v_cmp_lt_u32_e32 vcc, s50, v106
	s_and_b64 exec, exec, vcc
	s_cbranch_execz .LBB0_419
	v_add_f32_e32 v92, v90, v91
	v_add_u32_e32 v90, s50, v46
	v_ashrrev_i32_e32 v91, 31, v90
	v_lshlrev_b64 v[90:91], 6, v[90:91]
	v_lshl_add_u64 v[90:91], s[58:59], 0, v[90:91]
	global_store_dword v[90:91], v92, off

.LBB0_426:
	v_swap_b32 v29, v34
	v_swap_b32 v33, v90
	s_waitcnt lgkmcnt(0)
	v_pk_mul_f32 v[134:135], v[28:29], v[24:25] op_sel_hi:[1,0]
	v_pk_fma_f32 v[134:135], v[34:35], v[24:25], v[134:135] op_sel:[0,1,0]
	v_pk_fma_f32 v[134:135], v[32:33], v[26:27], v[134:135] op_sel_hi:[1,0,1]
	v_pk_fma_f32 v[134:135], v[90:91], v[26:27], v[134:135] op_sel:[0,1,0]
	v_pk_fma_f32 v[28:29], v[20:21], v[30:31], v[28:29] op_sel_hi:[0,1,1]
	v_pk_fma_f32 v[34:35], v[20:21], v[30:31], v[34:35] op_sel:[1,0,0]
	v_add_f32_dpp v134, v134, v134 quad_perm:[1,0,3,2] row_mask:0xf bank_mask:0xf bound_ctrl:1
	v_add_f32_dpp v135, v135, v135 quad_perm:[1,0,3,2] row_mask:0xf bank_mask:0xf bound_ctrl:1
	v_pk_fma_f32 v[32:33], v[22:23], v[30:31], v[32:33] op_sel_hi:[0,1,1]
	v_add_f32_dpp v134, v134, v134 quad_perm:[2,3,0,1] row_mask:0xf bank_mask:0xf bound_ctrl:1
	v_add_f32_dpp v135, v135, v135 quad_perm:[2,3,0,1] row_mask:0xf bank_mask:0xf bound_ctrl:1
	v_pk_fma_f32 v[90:91], v[22:23], v[30:31], v[90:91] op_sel:[1,0,0]
	v_add_f32_dpp v134, v134, v134 row_half_mirror row_mask:0xf bank_mask:0xf bound_ctrl:1
	v_add_f32_dpp v135, v135, v135 row_half_mirror row_mask:0xf bank_mask:0xf bound_ctrl:1
	ds_read_b64 v[30:31], v95 offset:20736
	ds_read_b128 v[116:119], v93 offset:12288
	ds_read_b128 v[120:123], v93 offset:16384
	ds_read_b128 v[124:127], v93 offset:8192
	ds_read_b128 v[130:133], v93
	ds_read_b64 v[96:97], v92
	v_add_f32_dpp v134, v134, v134 row_mirror row_mask:0xf bank_mask:0xf bound_ctrl:1
	v_add_f32_dpp v135, v135, v135 row_mirror row_mask:0xf bank_mask:0xf bound_ctrl:1
	v_pk_fma_f32 v[28:29], v[16:17], v[134:135], v[28:29] op_sel_hi:[0,1,1]
	v_pk_fma_f32 v[34:35], v[16:17], v[134:135], v[34:35] op_sel:[1,0,0]
	v_pk_fma_f32 v[32:33], v[18:19], v[134:135], v[32:33] op_sel_hi:[0,1,1]
	v_pk_fma_f32 v[90:91], v[18:19], v[134:135], v[90:91] op_sel:[1,0,0]
	s_waitcnt lgkmcnt(4)
	v_pk_mul_f32 v[134:135], v[28:29], v[116:117] op_sel_hi:[1,0]
	v_pk_mul_f32 v[16:17], v[28:29], v[12:13] op_sel_hi:[1,0]
	v_pk_fma_f32 v[134:135], v[34:35], v[116:117], v[134:135] op_sel:[0,1,0]
	v_pk_fma_f32 v[16:17], v[34:35], v[12:13], v[16:17] op_sel:[0,1,0]
	v_pk_fma_f32 v[134:135], v[32:33], v[118:119], v[134:135] op_sel_hi:[1,0,1]
	v_pk_fma_f32 v[16:17], v[32:33], v[14:15], v[16:17] op_sel_hi:[1,0,1]
	v_pk_fma_f32 v[134:135], v[90:91], v[118:119], v[134:135] op_sel:[0,1,0]
	v_pk_fma_f32 v[16:17], v[90:91], v[14:15], v[16:17] op_sel:[0,1,0]
	v_cvt_pk_f16_f32 v16, v16, v17
	v_add_f32_dpp v134, v134, v134 quad_perm:[1,0,3,2] row_mask:0xf bank_mask:0xf bound_ctrl:1
	v_add_f32_dpp v135, v135, v135 quad_perm:[1,0,3,2] row_mask:0xf bank_mask:0xf bound_ctrl:1
	ds_write_b32 v42, v16
	ds_read_b128 v[24:27], v94 offset:12800
	ds_read_b128 v[16:19], v94 offset:16896
	ds_read_b128 v[20:23], v94 offset:8704
	ds_read_b128 v[12:15], v94 offset:512
	s_waitcnt lgkmcnt(5)
	v_pk_fma_f32 v[28:29], v[124:125], v[96:97], v[28:29] op_sel_hi:[0,1,1]
	v_add_f32_dpp v134, v134, v134 quad_perm:[2,3,0,1] row_mask:0xf bank_mask:0xf bound_ctrl:1
	v_add_f32_dpp v135, v135, v135 quad_perm:[2,3,0,1] row_mask:0xf bank_mask:0xf bound_ctrl:1
	v_pk_fma_f32 v[34:35], v[124:125], v[96:97], v[34:35] op_sel:[1,0,0]
	v_add_f32_dpp v134, v134, v134 row_half_mirror row_mask:0xf bank_mask:0xf bound_ctrl:1
	v_add_f32_dpp v135, v135, v135 row_half_mirror row_mask:0xf bank_mask:0xf bound_ctrl:1
	v_pk_fma_f32 v[32:33], v[126:127], v[96:97], v[32:33] op_sel_hi:[0,1,1]
	v_pk_fma_f32 v[90:91], v[126:127], v[96:97], v[90:91] op_sel:[1,0,0]
	v_add_f32_dpp v134, v134, v134 row_mirror row_mask:0xf bank_mask:0xf bound_ctrl:1
	v_add_f32_dpp v135, v135, v135 row_mirror row_mask:0xf bank_mask:0xf bound_ctrl:1
	v_pk_fma_f32 v[28:29], v[120:121], v[134:135], v[28:29] op_sel_hi:[0,1,1]
	v_pk_fma_f32 v[34:35], v[120:121], v[134:135], v[34:35] op_sel:[1,0,0]
	v_pk_fma_f32 v[32:33], v[122:123], v[134:135], v[32:33] op_sel_hi:[0,1,1]
	v_pk_fma_f32 v[90:91], v[122:123], v[134:135], v[90:91] op_sel:[1,0,0]
	s_waitcnt lgkmcnt(0)
	v_pk_mul_f32 v[134:135], v[28:29], v[24:25] op_sel_hi:[1,0]
	v_pk_mul_f32 v[116:117], v[28:29], v[130:131] op_sel_hi:[1,0]
	v_pk_fma_f32 v[134:135], v[34:35], v[24:25], v[134:135] op_sel:[0,1,0]
	v_pk_fma_f32 v[116:117], v[34:35], v[130:131], v[116:117] op_sel:[0,1,0]
	v_pk_fma_f32 v[134:135], v[32:33], v[26:27], v[134:135] op_sel_hi:[1,0,1]
	v_pk_fma_f32 v[116:117], v[32:33], v[132:133], v[116:117] op_sel_hi:[1,0,1]
	v_pk_fma_f32 v[134:135], v[90:91], v[26:27], v[134:135] op_sel:[0,1,0]
	v_pk_fma_f32 v[116:117], v[90:91], v[132:133], v[116:117] op_sel:[0,1,0]
	v_cvt_pk_f16_f32 v116, v116, v117
	v_add_f32_dpp v134, v134, v134 quad_perm:[1,0,3,2] row_mask:0xf bank_mask:0xf bound_ctrl:1
	v_add_f32_dpp v135, v135, v135 quad_perm:[1,0,3,2] row_mask:0xf bank_mask:0xf bound_ctrl:1
	ds_write_b32 v42, v116 offset:1024
	v_pk_fma_f32 v[28:29], v[20:21], v[30:31], v[28:29] op_sel_hi:[0,1,1]
	v_add_f32_dpp v134, v134, v134 quad_perm:[2,3,0,1] row_mask:0xf bank_mask:0xf bound_ctrl:1
	v_add_f32_dpp v135, v135, v135 quad_perm:[2,3,0,1] row_mask:0xf bank_mask:0xf bound_ctrl:1
	v_pk_fma_f32 v[34:35], v[20:21], v[30:31], v[34:35] op_sel:[1,0,0]
	v_add_f32_dpp v134, v134, v134 row_half_mirror row_mask:0xf bank_mask:0xf bound_ctrl:1
	v_add_f32_dpp v135, v135, v135 row_half_mirror row_mask:0xf bank_mask:0xf bound_ctrl:1
	v_pk_fma_f32 v[32:33], v[22:23], v[30:31], v[32:33] op_sel_hi:[0,1,1]
	v_pk_fma_f32 v[90:91], v[22:23], v[30:31], v[90:91] op_sel:[1,0,0]
	ds_read_b64 v[30:31], v95 offset:20992
	ds_read_b128 v[116:119], v93 offset:12800
	ds_read_b128 v[120:123], v93 offset:16896
	ds_read_b128 v[124:127], v93 offset:8704
	ds_read_b128 v[130:133], v93 offset:512
	ds_read_b64 v[96:97], v92 offset:256
	v_add_f32_dpp v134, v134, v134 row_mirror row_mask:0xf bank_mask:0xf bound_ctrl:1
	v_add_f32_dpp v135, v135, v135 row_mirror row_mask:0xf bank_mask:0xf bound_ctrl:1
	v_pk_fma_f32 v[28:29], v[16:17], v[134:135], v[28:29] op_sel_hi:[0,1,1]
	v_pk_fma_f32 v[34:35], v[16:17], v[134:135], v[34:35] op_sel:[1,0,0]
	v_pk_fma_f32 v[32:33], v[18:19], v[134:135], v[32:33] op_sel_hi:[0,1,1]
	v_pk_fma_f32 v[90:91], v[18:19], v[134:135], v[90:91] op_sel:[1,0,0]
	s_waitcnt lgkmcnt(4)
	v_pk_mul_f32 v[134:135], v[28:29], v[116:117] op_sel_hi:[1,0]
	v_pk_mul_f32 v[16:17], v[28:29], v[12:13] op_sel_hi:[1,0]
	v_pk_fma_f32 v[134:135], v[34:35], v[116:117], v[134:135] op_sel:[0,1,0]
	v_pk_fma_f32 v[16:17], v[34:35], v[12:13], v[16:17] op_sel:[0,1,0]
	v_pk_fma_f32 v[134:135], v[32:33], v[118:119], v[134:135] op_sel_hi:[1,0,1]
	v_pk_fma_f32 v[16:17], v[32:33], v[14:15], v[16:17] op_sel_hi:[1,0,1]
	v_pk_fma_f32 v[134:135], v[90:91], v[118:119], v[134:135] op_sel:[0,1,0]
	v_pk_fma_f32 v[16:17], v[90:91], v[14:15], v[16:17] op_sel:[0,1,0]
	v_cvt_pk_f16_f32 v16, v16, v17
	v_add_f32_dpp v134, v134, v134 quad_perm:[1,0,3,2] row_mask:0xf bank_mask:0xf bound_ctrl:1
	v_add_f32_dpp v135, v135, v135 quad_perm:[1,0,3,2] row_mask:0xf bank_mask:0xf bound_ctrl:1
	ds_write_b32 v42, v16 offset:2048
	ds_read_b128 v[24:27], v94 offset:13312
	ds_read_b128 v[16:19], v94 offset:17408
	ds_read_b128 v[20:23], v94 offset:9216
	ds_read_b128 v[12:15], v94 offset:1024
	s_waitcnt lgkmcnt(5)
	v_pk_fma_f32 v[28:29], v[124:125], v[96:97], v[28:29] op_sel_hi:[0,1,1]
	v_add_f32_dpp v134, v134, v134 quad_perm:[2,3,0,1] row_mask:0xf bank_mask:0xf bound_ctrl:1
	v_add_f32_dpp v135, v135, v135 quad_perm:[2,3,0,1] row_mask:0xf bank_mask:0xf bound_ctrl:1
	v_pk_fma_f32 v[34:35], v[124:125], v[96:97], v[34:35] op_sel:[1,0,0]
	v_add_f32_dpp v134, v134, v134 row_half_mirror row_mask:0xf bank_mask:0xf bound_ctrl:1
	v_add_f32_dpp v135, v135, v135 row_half_mirror row_mask:0xf bank_mask:0xf bound_ctrl:1
	v_pk_fma_f32 v[32:33], v[126:127], v[96:97], v[32:33] op_sel_hi:[0,1,1]
	v_pk_fma_f32 v[90:91], v[126:127], v[96:97], v[90:91] op_sel:[1,0,0]
	v_add_f32_dpp v134, v134, v134 row_mirror row_mask:0xf bank_mask:0xf bound_ctrl:1
	v_add_f32_dpp v135, v135, v135 row_mirror row_mask:0xf bank_mask:0xf bound_ctrl:1
	v_pk_fma_f32 v[28:29], v[120:121], v[134:135], v[28:29] op_sel_hi:[0,1,1]
	v_pk_fma_f32 v[34:35], v[120:121], v[134:135], v[34:35] op_sel:[1,0,0]
	v_pk_fma_f32 v[32:33], v[122:123], v[134:135], v[32:33] op_sel_hi:[0,1,1]
	v_pk_fma_f32 v[90:91], v[122:123], v[134:135], v[90:91] op_sel:[1,0,0]
	s_waitcnt lgkmcnt(0)
	v_pk_mul_f32 v[134:135], v[28:29], v[24:25] op_sel_hi:[1,0]
	v_pk_mul_f32 v[116:117], v[28:29], v[130:131] op_sel_hi:[1,0]
	v_pk_fma_f32 v[134:135], v[34:35], v[24:25], v[134:135] op_sel:[0,1,0]
	v_pk_fma_f32 v[116:117], v[34:35], v[130:131], v[116:117] op_sel:[0,1,0]
	v_pk_fma_f32 v[134:135], v[32:33], v[26:27], v[134:135] op_sel_hi:[1,0,1]
	v_pk_fma_f32 v[116:117], v[32:33], v[132:133], v[116:117] op_sel_hi:[1,0,1]
	v_pk_fma_f32 v[134:135], v[90:91], v[26:27], v[134:135] op_sel:[0,1,0]
	v_pk_fma_f32 v[116:117], v[90:91], v[132:133], v[116:117] op_sel:[0,1,0]
	v_cvt_pk_f16_f32 v116, v116, v117
	v_add_f32_dpp v134, v134, v134 quad_perm:[1,0,3,2] row_mask:0xf bank_mask:0xf bound_ctrl:1
	v_add_f32_dpp v135, v135, v135 quad_perm:[1,0,3,2] row_mask:0xf bank_mask:0xf bound_ctrl:1
	ds_write_b32 v42, v116 offset:3072
	v_pk_fma_f32 v[28:29], v[20:21], v[30:31], v[28:29] op_sel_hi:[0,1,1]
	v_add_f32_dpp v134, v134, v134 quad_perm:[2,3,0,1] row_mask:0xf bank_mask:0xf bound_ctrl:1
	v_add_f32_dpp v135, v135, v135 quad_perm:[2,3,0,1] row_mask:0xf bank_mask:0xf bound_ctrl:1
	v_pk_fma_f32 v[34:35], v[20:21], v[30:31], v[34:35] op_sel:[1,0,0]
	v_add_f32_dpp v134, v134, v134 row_half_mirror row_mask:0xf bank_mask:0xf bound_ctrl:1
	v_add_f32_dpp v135, v135, v135 row_half_mirror row_mask:0xf bank_mask:0xf bound_ctrl:1
	v_pk_fma_f32 v[32:33], v[22:23], v[30:31], v[32:33] op_sel_hi:[0,1,1]
	v_pk_fma_f32 v[90:91], v[22:23], v[30:31], v[90:91] op_sel:[1,0,0]
	ds_read_b64 v[30:31], v95 offset:21248
	ds_read_b128 v[116:119], v93 offset:13312
	ds_read_b128 v[120:123], v93 offset:17408
	ds_read_b128 v[124:127], v93 offset:9216
	ds_read_b128 v[130:133], v93 offset:1024
	ds_read_b64 v[96:97], v92 offset:512
	v_add_f32_dpp v134, v134, v134 row_mirror row_mask:0xf bank_mask:0xf bound_ctrl:1
	v_add_f32_dpp v135, v135, v135 row_mirror row_mask:0xf bank_mask:0xf bound_ctrl:1
	v_pk_fma_f32 v[28:29], v[16:17], v[134:135], v[28:29] op_sel_hi:[0,1,1]
	v_pk_fma_f32 v[34:35], v[16:17], v[134:135], v[34:35] op_sel:[1,0,0]
	v_pk_fma_f32 v[32:33], v[18:19], v[134:135], v[32:33] op_sel_hi:[0,1,1]
	v_pk_fma_f32 v[90:91], v[18:19], v[134:135], v[90:91] op_sel:[1,0,0]
	s_waitcnt lgkmcnt(4)
	v_pk_mul_f32 v[134:135], v[28:29], v[116:117] op_sel_hi:[1,0]
	v_pk_mul_f32 v[16:17], v[28:29], v[12:13] op_sel_hi:[1,0]
	v_pk_fma_f32 v[134:135], v[34:35], v[116:117], v[134:135] op_sel:[0,1,0]
	v_pk_fma_f32 v[16:17], v[34:35], v[12:13], v[16:17] op_sel:[0,1,0]
	v_pk_fma_f32 v[134:135], v[32:33], v[118:119], v[134:135] op_sel_hi:[1,0,1]
	v_pk_fma_f32 v[16:17], v[32:33], v[14:15], v[16:17] op_sel_hi:[1,0,1]
	v_pk_fma_f32 v[134:135], v[90:91], v[118:119], v[134:135] op_sel:[0,1,0]
	v_pk_fma_f32 v[16:17], v[90:91], v[14:15], v[16:17] op_sel:[0,1,0]
	v_cvt_pk_f16_f32 v16, v16, v17
	v_add_f32_dpp v134, v134, v134 quad_perm:[1,0,3,2] row_mask:0xf bank_mask:0xf bound_ctrl:1
	v_add_f32_dpp v135, v135, v135 quad_perm:[1,0,3,2] row_mask:0xf bank_mask:0xf bound_ctrl:1
	ds_write_b32 v42, v16 offset:4096
	ds_read_b128 v[24:27], v94 offset:13824
	ds_read_b128 v[16:19], v94 offset:17920
	ds_read_b128 v[20:23], v94 offset:9728
	ds_read_b128 v[12:15], v94 offset:1536
	s_waitcnt lgkmcnt(5)
	v_pk_fma_f32 v[28:29], v[124:125], v[96:97], v[28:29] op_sel_hi:[0,1,1]
	v_add_f32_dpp v134, v134, v134 quad_perm:[2,3,0,1] row_mask:0xf bank_mask:0xf bound_ctrl:1
	v_add_f32_dpp v135, v135, v135 quad_perm:[2,3,0,1] row_mask:0xf bank_mask:0xf bound_ctrl:1
	v_pk_fma_f32 v[34:35], v[124:125], v[96:97], v[34:35] op_sel:[1,0,0]
	v_add_f32_dpp v134, v134, v134 row_half_mirror row_mask:0xf bank_mask:0xf bound_ctrl:1
	v_add_f32_dpp v135, v135, v135 row_half_mirror row_mask:0xf bank_mask:0xf bound_ctrl:1
	v_pk_fma_f32 v[32:33], v[126:127], v[96:97], v[32:33] op_sel_hi:[0,1,1]
	v_pk_fma_f32 v[90:91], v[126:127], v[96:97], v[90:91] op_sel:[1,0,0]
	v_add_f32_dpp v134, v134, v134 row_mirror row_mask:0xf bank_mask:0xf bound_ctrl:1
	v_add_f32_dpp v135, v135, v135 row_mirror row_mask:0xf bank_mask:0xf bound_ctrl:1
	v_pk_fma_f32 v[28:29], v[120:121], v[134:135], v[28:29] op_sel_hi:[0,1,1]
	v_pk_fma_f32 v[34:35], v[120:121], v[134:135], v[34:35] op_sel:[1,0,0]
	v_pk_fma_f32 v[32:33], v[122:123], v[134:135], v[32:33] op_sel_hi:[0,1,1]
	v_pk_fma_f32 v[90:91], v[122:123], v[134:135], v[90:91] op_sel:[1,0,0]
	s_waitcnt lgkmcnt(0)
	v_pk_mul_f32 v[134:135], v[28:29], v[24:25] op_sel_hi:[1,0]
	v_pk_mul_f32 v[116:117], v[28:29], v[130:131] op_sel_hi:[1,0]
	v_pk_fma_f32 v[134:135], v[34:35], v[24:25], v[134:135] op_sel:[0,1,0]
	v_pk_fma_f32 v[116:117], v[34:35], v[130:131], v[116:117] op_sel:[0,1,0]
	v_pk_fma_f32 v[134:135], v[32:33], v[26:27], v[134:135] op_sel_hi:[1,0,1]
	v_pk_fma_f32 v[116:117], v[32:33], v[132:133], v[116:117] op_sel_hi:[1,0,1]
	v_pk_fma_f32 v[134:135], v[90:91], v[26:27], v[134:135] op_sel:[0,1,0]
	v_pk_fma_f32 v[116:117], v[90:91], v[132:133], v[116:117] op_sel:[0,1,0]
	v_cvt_pk_f16_f32 v116, v116, v117
	v_add_f32_dpp v134, v134, v134 quad_perm:[1,0,3,2] row_mask:0xf bank_mask:0xf bound_ctrl:1
	v_add_f32_dpp v135, v135, v135 quad_perm:[1,0,3,2] row_mask:0xf bank_mask:0xf bound_ctrl:1
	ds_write_b32 v42, v116 offset:5120
	v_pk_fma_f32 v[28:29], v[20:21], v[30:31], v[28:29] op_sel_hi:[0,1,1]
	v_add_f32_dpp v134, v134, v134 quad_perm:[2,3,0,1] row_mask:0xf bank_mask:0xf bound_ctrl:1
	v_add_f32_dpp v135, v135, v135 quad_perm:[2,3,0,1] row_mask:0xf bank_mask:0xf bound_ctrl:1
	v_pk_fma_f32 v[34:35], v[20:21], v[30:31], v[34:35] op_sel:[1,0,0]
	v_add_f32_dpp v134, v134, v134 row_half_mirror row_mask:0xf bank_mask:0xf bound_ctrl:1
	v_add_f32_dpp v135, v135, v135 row_half_mirror row_mask:0xf bank_mask:0xf bound_ctrl:1
	v_pk_fma_f32 v[32:33], v[22:23], v[30:31], v[32:33] op_sel_hi:[0,1,1]
	v_pk_fma_f32 v[90:91], v[22:23], v[30:31], v[90:91] op_sel:[1,0,0]
	ds_read_b64 v[30:31], v95 offset:21504
	ds_read_b128 v[116:119], v93 offset:13824
	ds_read_b128 v[120:123], v93 offset:17920
	ds_read_b128 v[124:127], v93 offset:9728
	ds_read_b128 v[130:133], v93 offset:1536
	ds_read_b64 v[96:97], v92 offset:768
	v_add_f32_dpp v134, v134, v134 row_mirror row_mask:0xf bank_mask:0xf bound_ctrl:1
	v_add_f32_dpp v135, v135, v135 row_mirror row_mask:0xf bank_mask:0xf bound_ctrl:1
	v_pk_fma_f32 v[28:29], v[16:17], v[134:135], v[28:29] op_sel_hi:[0,1,1]
	v_pk_fma_f32 v[34:35], v[16:17], v[134:135], v[34:35] op_sel:[1,0,0]
	v_pk_fma_f32 v[32:33], v[18:19], v[134:135], v[32:33] op_sel_hi:[0,1,1]
	v_pk_fma_f32 v[90:91], v[18:19], v[134:135], v[90:91] op_sel:[1,0,0]
	s_waitcnt lgkmcnt(4)
	v_pk_mul_f32 v[134:135], v[28:29], v[116:117] op_sel_hi:[1,0]
	v_pk_mul_f32 v[16:17], v[28:29], v[12:13] op_sel_hi:[1,0]
	v_pk_fma_f32 v[134:135], v[34:35], v[116:117], v[134:135] op_sel:[0,1,0]
	v_pk_fma_f32 v[16:17], v[34:35], v[12:13], v[16:17] op_sel:[0,1,0]
	v_pk_fma_f32 v[134:135], v[32:33], v[118:119], v[134:135] op_sel_hi:[1,0,1]
	v_pk_fma_f32 v[16:17], v[32:33], v[14:15], v[16:17] op_sel_hi:[1,0,1]
	v_pk_fma_f32 v[134:135], v[90:91], v[118:119], v[134:135] op_sel:[0,1,0]
	v_pk_fma_f32 v[16:17], v[90:91], v[14:15], v[16:17] op_sel:[0,1,0]
	v_cvt_pk_f16_f32 v16, v16, v17
	v_add_f32_dpp v134, v134, v134 quad_perm:[1,0,3,2] row_mask:0xf bank_mask:0xf bound_ctrl:1
	v_add_f32_dpp v135, v135, v135 quad_perm:[1,0,3,2] row_mask:0xf bank_mask:0xf bound_ctrl:1
	ds_write_b32 v42, v16 offset:6144
	ds_read_b128 v[24:27], v94 offset:14336
	ds_read_b128 v[16:19], v94 offset:18432
	ds_read_b128 v[20:23], v94 offset:10240
	ds_read_b128 v[12:15], v94 offset:2048
	s_waitcnt lgkmcnt(5)
	v_pk_fma_f32 v[28:29], v[124:125], v[96:97], v[28:29] op_sel_hi:[0,1,1]
	v_add_f32_dpp v134, v134, v134 quad_perm:[2,3,0,1] row_mask:0xf bank_mask:0xf bound_ctrl:1
	v_add_f32_dpp v135, v135, v135 quad_perm:[2,3,0,1] row_mask:0xf bank_mask:0xf bound_ctrl:1
	v_pk_fma_f32 v[34:35], v[124:125], v[96:97], v[34:35] op_sel:[1,0,0]
	v_add_f32_dpp v134, v134, v134 row_half_mirror row_mask:0xf bank_mask:0xf bound_ctrl:1
	v_add_f32_dpp v135, v135, v135 row_half_mirror row_mask:0xf bank_mask:0xf bound_ctrl:1
	v_pk_fma_f32 v[32:33], v[126:127], v[96:97], v[32:33] op_sel_hi:[0,1,1]
	v_pk_fma_f32 v[90:91], v[126:127], v[96:97], v[90:91] op_sel:[1,0,0]
	v_add_f32_dpp v134, v134, v134 row_mirror row_mask:0xf bank_mask:0xf bound_ctrl:1
	v_add_f32_dpp v135, v135, v135 row_mirror row_mask:0xf bank_mask:0xf bound_ctrl:1
	v_pk_fma_f32 v[28:29], v[120:121], v[134:135], v[28:29] op_sel_hi:[0,1,1]
	v_pk_fma_f32 v[34:35], v[120:121], v[134:135], v[34:35] op_sel:[1,0,0]
	v_pk_fma_f32 v[32:33], v[122:123], v[134:135], v[32:33] op_sel_hi:[0,1,1]
	v_pk_fma_f32 v[90:91], v[122:123], v[134:135], v[90:91] op_sel:[1,0,0]
	s_waitcnt lgkmcnt(0)
	v_pk_mul_f32 v[134:135], v[28:29], v[24:25] op_sel_hi:[1,0]
	v_pk_mul_f32 v[116:117], v[28:29], v[130:131] op_sel_hi:[1,0]
	v_pk_fma_f32 v[134:135], v[34:35], v[24:25], v[134:135] op_sel:[0,1,0]
	v_pk_fma_f32 v[116:117], v[34:35], v[130:131], v[116:117] op_sel:[0,1,0]
	v_pk_fma_f32 v[134:135], v[32:33], v[26:27], v[134:135] op_sel_hi:[1,0,1]
	v_pk_fma_f32 v[116:117], v[32:33], v[132:133], v[116:117] op_sel_hi:[1,0,1]
	v_pk_fma_f32 v[134:135], v[90:91], v[26:27], v[134:135] op_sel:[0,1,0]
	v_pk_fma_f32 v[116:117], v[90:91], v[132:133], v[116:117] op_sel:[0,1,0]
	v_cvt_pk_f16_f32 v116, v116, v117
	v_add_f32_dpp v134, v134, v134 quad_perm:[1,0,3,2] row_mask:0xf bank_mask:0xf bound_ctrl:1
	v_add_f32_dpp v135, v135, v135 quad_perm:[1,0,3,2] row_mask:0xf bank_mask:0xf bound_ctrl:1
	ds_write_b32 v42, v116 offset:7168
	v_pk_fma_f32 v[28:29], v[20:21], v[30:31], v[28:29] op_sel_hi:[0,1,1]
	v_add_f32_dpp v134, v134, v134 quad_perm:[2,3,0,1] row_mask:0xf bank_mask:0xf bound_ctrl:1
	v_add_f32_dpp v135, v135, v135 quad_perm:[2,3,0,1] row_mask:0xf bank_mask:0xf bound_ctrl:1
	v_pk_fma_f32 v[34:35], v[20:21], v[30:31], v[34:35] op_sel:[1,0,0]
	v_add_f32_dpp v134, v134, v134 row_half_mirror row_mask:0xf bank_mask:0xf bound_ctrl:1
	v_add_f32_dpp v135, v135, v135 row_half_mirror row_mask:0xf bank_mask:0xf bound_ctrl:1
	v_pk_fma_f32 v[32:33], v[22:23], v[30:31], v[32:33] op_sel_hi:[0,1,1]
	v_pk_fma_f32 v[90:91], v[22:23], v[30:31], v[90:91] op_sel:[1,0,0]
	ds_read_b64 v[30:31], v95 offset:21760
	ds_read_b128 v[116:119], v93 offset:14336
	ds_read_b128 v[120:123], v93 offset:18432
	ds_read_b128 v[124:127], v93 offset:10240
	ds_read_b128 v[130:133], v93 offset:2048
	ds_read_b64 v[96:97], v92 offset:1024
	v_add_f32_dpp v134, v134, v134 row_mirror row_mask:0xf bank_mask:0xf bound_ctrl:1
	v_add_f32_dpp v135, v135, v135 row_mirror row_mask:0xf bank_mask:0xf bound_ctrl:1
	v_pk_fma_f32 v[28:29], v[16:17], v[134:135], v[28:29] op_sel_hi:[0,1,1]
	v_pk_fma_f32 v[34:35], v[16:17], v[134:135], v[34:35] op_sel:[1,0,0]
	v_pk_fma_f32 v[32:33], v[18:19], v[134:135], v[32:33] op_sel_hi:[0,1,1]
	v_pk_fma_f32 v[90:91], v[18:19], v[134:135], v[90:91] op_sel:[1,0,0]
	s_waitcnt lgkmcnt(4)
	v_pk_mul_f32 v[134:135], v[28:29], v[116:117] op_sel_hi:[1,0]
	v_pk_mul_f32 v[16:17], v[28:29], v[12:13] op_sel_hi:[1,0]
	v_pk_fma_f32 v[134:135], v[34:35], v[116:117], v[134:135] op_sel:[0,1,0]
	v_pk_fma_f32 v[16:17], v[34:35], v[12:13], v[16:17] op_sel:[0,1,0]
	v_pk_fma_f32 v[134:135], v[32:33], v[118:119], v[134:135] op_sel_hi:[1,0,1]
	v_pk_fma_f32 v[16:17], v[32:33], v[14:15], v[16:17] op_sel_hi:[1,0,1]
	v_pk_fma_f32 v[134:135], v[90:91], v[118:119], v[134:135] op_sel:[0,1,0]
	v_pk_fma_f32 v[16:17], v[90:91], v[14:15], v[16:17] op_sel:[0,1,0]
	v_cvt_pk_f16_f32 v16, v16, v17
	v_add_f32_dpp v134, v134, v134 quad_perm:[1,0,3,2] row_mask:0xf bank_mask:0xf bound_ctrl:1
	v_add_f32_dpp v135, v135, v135 quad_perm:[1,0,3,2] row_mask:0xf bank_mask:0xf bound_ctrl:1
	ds_write_b32 v42, v16 offset:8192
	ds_read_b128 v[24:27], v94 offset:14848
	ds_read_b128 v[16:19], v94 offset:18944
	ds_read_b128 v[20:23], v94 offset:10752
	ds_read_b128 v[12:15], v94 offset:2560
	s_waitcnt lgkmcnt(5)
	v_pk_fma_f32 v[28:29], v[124:125], v[96:97], v[28:29] op_sel_hi:[0,1,1]
	v_add_f32_dpp v134, v134, v134 quad_perm:[2,3,0,1] row_mask:0xf bank_mask:0xf bound_ctrl:1
	v_add_f32_dpp v135, v135, v135 quad_perm:[2,3,0,1] row_mask:0xf bank_mask:0xf bound_ctrl:1
	v_pk_fma_f32 v[34:35], v[124:125], v[96:97], v[34:35] op_sel:[1,0,0]
	v_add_f32_dpp v134, v134, v134 row_half_mirror row_mask:0xf bank_mask:0xf bound_ctrl:1
	v_add_f32_dpp v135, v135, v135 row_half_mirror row_mask:0xf bank_mask:0xf bound_ctrl:1
	v_pk_fma_f32 v[32:33], v[126:127], v[96:97], v[32:33] op_sel_hi:[0,1,1]
	v_pk_fma_f32 v[90:91], v[126:127], v[96:97], v[90:91] op_sel:[1,0,0]
	v_add_f32_dpp v134, v134, v134 row_mirror row_mask:0xf bank_mask:0xf bound_ctrl:1
	v_add_f32_dpp v135, v135, v135 row_mirror row_mask:0xf bank_mask:0xf bound_ctrl:1
	v_pk_fma_f32 v[28:29], v[120:121], v[134:135], v[28:29] op_sel_hi:[0,1,1]
	v_pk_fma_f32 v[34:35], v[120:121], v[134:135], v[34:35] op_sel:[1,0,0]
	v_pk_fma_f32 v[32:33], v[122:123], v[134:135], v[32:33] op_sel_hi:[0,1,1]
	v_pk_fma_f32 v[90:91], v[122:123], v[134:135], v[90:91] op_sel:[1,0,0]
	s_waitcnt lgkmcnt(0)
	v_pk_mul_f32 v[134:135], v[28:29], v[24:25] op_sel_hi:[1,0]
	v_pk_mul_f32 v[116:117], v[28:29], v[130:131] op_sel_hi:[1,0]
	v_pk_fma_f32 v[134:135], v[34:35], v[24:25], v[134:135] op_sel:[0,1,0]
	v_pk_fma_f32 v[116:117], v[34:35], v[130:131], v[116:117] op_sel:[0,1,0]
	v_pk_fma_f32 v[134:135], v[32:33], v[26:27], v[134:135] op_sel_hi:[1,0,1]
	v_pk_fma_f32 v[116:117], v[32:33], v[132:133], v[116:117] op_sel_hi:[1,0,1]
	v_pk_fma_f32 v[134:135], v[90:91], v[26:27], v[134:135] op_sel:[0,1,0]
	v_pk_fma_f32 v[116:117], v[90:91], v[132:133], v[116:117] op_sel:[0,1,0]
	v_cvt_pk_f16_f32 v116, v116, v117
	v_add_f32_dpp v134, v134, v134 quad_perm:[1,0,3,2] row_mask:0xf bank_mask:0xf bound_ctrl:1
	v_add_f32_dpp v135, v135, v135 quad_perm:[1,0,3,2] row_mask:0xf bank_mask:0xf bound_ctrl:1
	ds_write_b32 v42, v116 offset:9216
	v_pk_fma_f32 v[28:29], v[20:21], v[30:31], v[28:29] op_sel_hi:[0,1,1]
	v_add_f32_dpp v134, v134, v134 quad_perm:[2,3,0,1] row_mask:0xf bank_mask:0xf bound_ctrl:1
	v_add_f32_dpp v135, v135, v135 quad_perm:[2,3,0,1] row_mask:0xf bank_mask:0xf bound_ctrl:1
	v_pk_fma_f32 v[34:35], v[20:21], v[30:31], v[34:35] op_sel:[1,0,0]
	v_add_f32_dpp v134, v134, v134 row_half_mirror row_mask:0xf bank_mask:0xf bound_ctrl:1
	v_add_f32_dpp v135, v135, v135 row_half_mirror row_mask:0xf bank_mask:0xf bound_ctrl:1
	v_pk_fma_f32 v[32:33], v[22:23], v[30:31], v[32:33] op_sel_hi:[0,1,1]
	v_pk_fma_f32 v[90:91], v[22:23], v[30:31], v[90:91] op_sel:[1,0,0]
	ds_read_b64 v[30:31], v95 offset:22016
	ds_read_b128 v[116:119], v93 offset:14848
	ds_read_b128 v[120:123], v93 offset:18944
	ds_read_b128 v[124:127], v93 offset:10752
	ds_read_b128 v[130:133], v93 offset:2560
	ds_read_b64 v[96:97], v92 offset:1280
	v_add_f32_dpp v134, v134, v134 row_mirror row_mask:0xf bank_mask:0xf bound_ctrl:1
	v_add_f32_dpp v135, v135, v135 row_mirror row_mask:0xf bank_mask:0xf bound_ctrl:1
	v_pk_fma_f32 v[28:29], v[16:17], v[134:135], v[28:29] op_sel_hi:[0,1,1]
	v_pk_fma_f32 v[34:35], v[16:17], v[134:135], v[34:35] op_sel:[1,0,0]
	v_pk_fma_f32 v[32:33], v[18:19], v[134:135], v[32:33] op_sel_hi:[0,1,1]
	v_pk_fma_f32 v[90:91], v[18:19], v[134:135], v[90:91] op_sel:[1,0,0]
	s_waitcnt lgkmcnt(4)
	v_pk_mul_f32 v[134:135], v[28:29], v[116:117] op_sel_hi:[1,0]
	v_pk_mul_f32 v[16:17], v[28:29], v[12:13] op_sel_hi:[1,0]
	v_pk_fma_f32 v[134:135], v[34:35], v[116:117], v[134:135] op_sel:[0,1,0]
	v_pk_fma_f32 v[16:17], v[34:35], v[12:13], v[16:17] op_sel:[0,1,0]
	v_pk_fma_f32 v[134:135], v[32:33], v[118:119], v[134:135] op_sel_hi:[1,0,1]
	v_pk_fma_f32 v[16:17], v[32:33], v[14:15], v[16:17] op_sel_hi:[1,0,1]
	v_pk_fma_f32 v[134:135], v[90:91], v[118:119], v[134:135] op_sel:[0,1,0]
	v_pk_fma_f32 v[16:17], v[90:91], v[14:15], v[16:17] op_sel:[0,1,0]
	v_cvt_pk_f16_f32 v16, v16, v17
	v_add_f32_dpp v134, v134, v134 quad_perm:[1,0,3,2] row_mask:0xf bank_mask:0xf bound_ctrl:1
	v_add_f32_dpp v135, v135, v135 quad_perm:[1,0,3,2] row_mask:0xf bank_mask:0xf bound_ctrl:1
	ds_write_b32 v42, v16 offset:10240
	ds_read_b128 v[24:27], v94 offset:15360
	ds_read_b128 v[16:19], v94 offset:19456
	ds_read_b128 v[20:23], v94 offset:11264
	ds_read_b128 v[12:15], v94 offset:3072
	s_waitcnt lgkmcnt(5)
	v_pk_fma_f32 v[28:29], v[124:125], v[96:97], v[28:29] op_sel_hi:[0,1,1]
	v_add_f32_dpp v134, v134, v134 quad_perm:[2,3,0,1] row_mask:0xf bank_mask:0xf bound_ctrl:1
	v_add_f32_dpp v135, v135, v135 quad_perm:[2,3,0,1] row_mask:0xf bank_mask:0xf bound_ctrl:1
	v_pk_fma_f32 v[34:35], v[124:125], v[96:97], v[34:35] op_sel:[1,0,0]
	v_add_f32_dpp v134, v134, v134 row_half_mirror row_mask:0xf bank_mask:0xf bound_ctrl:1
	v_add_f32_dpp v135, v135, v135 row_half_mirror row_mask:0xf bank_mask:0xf bound_ctrl:1
	v_pk_fma_f32 v[32:33], v[126:127], v[96:97], v[32:33] op_sel_hi:[0,1,1]
	v_pk_fma_f32 v[90:91], v[126:127], v[96:97], v[90:91] op_sel:[1,0,0]
	v_add_f32_dpp v134, v134, v134 row_mirror row_mask:0xf bank_mask:0xf bound_ctrl:1
	v_add_f32_dpp v135, v135, v135 row_mirror row_mask:0xf bank_mask:0xf bound_ctrl:1
	v_pk_fma_f32 v[28:29], v[120:121], v[134:135], v[28:29] op_sel_hi:[0,1,1]
	v_pk_fma_f32 v[34:35], v[120:121], v[134:135], v[34:35] op_sel:[1,0,0]
	v_pk_fma_f32 v[32:33], v[122:123], v[134:135], v[32:33] op_sel_hi:[0,1,1]
	v_pk_fma_f32 v[90:91], v[122:123], v[134:135], v[90:91] op_sel:[1,0,0]
	s_waitcnt lgkmcnt(0)
	v_pk_mul_f32 v[134:135], v[28:29], v[24:25] op_sel_hi:[1,0]
	v_pk_mul_f32 v[116:117], v[28:29], v[130:131] op_sel_hi:[1,0]
	v_pk_fma_f32 v[134:135], v[34:35], v[24:25], v[134:135] op_sel:[0,1,0]
	v_pk_fma_f32 v[116:117], v[34:35], v[130:131], v[116:117] op_sel:[0,1,0]
	v_pk_fma_f32 v[134:135], v[32:33], v[26:27], v[134:135] op_sel_hi:[1,0,1]
	v_pk_fma_f32 v[116:117], v[32:33], v[132:133], v[116:117] op_sel_hi:[1,0,1]
	v_pk_fma_f32 v[134:135], v[90:91], v[26:27], v[134:135] op_sel:[0,1,0]
	v_pk_fma_f32 v[116:117], v[90:91], v[132:133], v[116:117] op_sel:[0,1,0]
	v_cvt_pk_f16_f32 v116, v116, v117
	v_add_f32_dpp v134, v134, v134 quad_perm:[1,0,3,2] row_mask:0xf bank_mask:0xf bound_ctrl:1
	v_add_f32_dpp v135, v135, v135 quad_perm:[1,0,3,2] row_mask:0xf bank_mask:0xf bound_ctrl:1
	ds_write_b32 v42, v116 offset:11264
	v_pk_fma_f32 v[28:29], v[20:21], v[30:31], v[28:29] op_sel_hi:[0,1,1]
	v_add_f32_dpp v134, v134, v134 quad_perm:[2,3,0,1] row_mask:0xf bank_mask:0xf bound_ctrl:1
	v_add_f32_dpp v135, v135, v135 quad_perm:[2,3,0,1] row_mask:0xf bank_mask:0xf bound_ctrl:1
	v_pk_fma_f32 v[34:35], v[20:21], v[30:31], v[34:35] op_sel:[1,0,0]
	v_add_f32_dpp v134, v134, v134 row_half_mirror row_mask:0xf bank_mask:0xf bound_ctrl:1
	v_add_f32_dpp v135, v135, v135 row_half_mirror row_mask:0xf bank_mask:0xf bound_ctrl:1
	v_pk_fma_f32 v[32:33], v[22:23], v[30:31], v[32:33] op_sel_hi:[0,1,1]
	v_pk_fma_f32 v[90:91], v[22:23], v[30:31], v[90:91] op_sel:[1,0,0]
	ds_read_b64 v[30:31], v95 offset:22272
	ds_read_b128 v[116:119], v93 offset:15360
	ds_read_b128 v[120:123], v93 offset:19456
	ds_read_b128 v[124:127], v93 offset:11264
	ds_read_b128 v[130:133], v93 offset:3072
	ds_read_b64 v[96:97], v92 offset:1536
	v_add_f32_dpp v134, v134, v134 row_mirror row_mask:0xf bank_mask:0xf bound_ctrl:1
	v_add_f32_dpp v135, v135, v135 row_mirror row_mask:0xf bank_mask:0xf bound_ctrl:1
	v_pk_fma_f32 v[28:29], v[16:17], v[134:135], v[28:29] op_sel_hi:[0,1,1]
	v_pk_fma_f32 v[34:35], v[16:17], v[134:135], v[34:35] op_sel:[1,0,0]
	v_pk_fma_f32 v[32:33], v[18:19], v[134:135], v[32:33] op_sel_hi:[0,1,1]
	v_pk_fma_f32 v[90:91], v[18:19], v[134:135], v[90:91] op_sel:[1,0,0]
	s_waitcnt lgkmcnt(4)
	v_pk_mul_f32 v[134:135], v[28:29], v[116:117] op_sel_hi:[1,0]
	v_pk_mul_f32 v[16:17], v[28:29], v[12:13] op_sel_hi:[1,0]
	v_pk_fma_f32 v[134:135], v[34:35], v[116:117], v[134:135] op_sel:[0,1,0]
	v_pk_fma_f32 v[16:17], v[34:35], v[12:13], v[16:17] op_sel:[0,1,0]
	v_pk_fma_f32 v[134:135], v[32:33], v[118:119], v[134:135] op_sel_hi:[1,0,1]
	v_pk_fma_f32 v[16:17], v[32:33], v[14:15], v[16:17] op_sel_hi:[1,0,1]
	v_pk_fma_f32 v[134:135], v[90:91], v[118:119], v[134:135] op_sel:[0,1,0]
	v_pk_fma_f32 v[16:17], v[90:91], v[14:15], v[16:17] op_sel:[0,1,0]
	v_cvt_pk_f16_f32 v16, v16, v17
	v_add_f32_dpp v134, v134, v134 quad_perm:[1,0,3,2] row_mask:0xf bank_mask:0xf bound_ctrl:1
	v_add_f32_dpp v135, v135, v135 quad_perm:[1,0,3,2] row_mask:0xf bank_mask:0xf bound_ctrl:1
	ds_write_b32 v42, v16 offset:12288
	ds_read_b128 v[24:27], v94 offset:15872
	ds_read_b128 v[16:19], v94 offset:19968
	ds_read_b128 v[20:23], v94 offset:11776
	ds_read_b128 v[12:15], v94 offset:3584
	s_waitcnt lgkmcnt(5)
	v_pk_fma_f32 v[28:29], v[124:125], v[96:97], v[28:29] op_sel_hi:[0,1,1]
	v_add_f32_dpp v134, v134, v134 quad_perm:[2,3,0,1] row_mask:0xf bank_mask:0xf bound_ctrl:1
	v_add_f32_dpp v135, v135, v135 quad_perm:[2,3,0,1] row_mask:0xf bank_mask:0xf bound_ctrl:1
	v_pk_fma_f32 v[34:35], v[124:125], v[96:97], v[34:35] op_sel:[1,0,0]
	v_add_f32_dpp v134, v134, v134 row_half_mirror row_mask:0xf bank_mask:0xf bound_ctrl:1
	v_add_f32_dpp v135, v135, v135 row_half_mirror row_mask:0xf bank_mask:0xf bound_ctrl:1
	v_pk_fma_f32 v[32:33], v[126:127], v[96:97], v[32:33] op_sel_hi:[0,1,1]
	v_pk_fma_f32 v[90:91], v[126:127], v[96:97], v[90:91] op_sel:[1,0,0]
	v_add_f32_dpp v134, v134, v134 row_mirror row_mask:0xf bank_mask:0xf bound_ctrl:1
	v_add_f32_dpp v135, v135, v135 row_mirror row_mask:0xf bank_mask:0xf bound_ctrl:1
	v_pk_fma_f32 v[28:29], v[120:121], v[134:135], v[28:29] op_sel_hi:[0,1,1]
	v_pk_fma_f32 v[34:35], v[120:121], v[134:135], v[34:35] op_sel:[1,0,0]
	v_pk_fma_f32 v[32:33], v[122:123], v[134:135], v[32:33] op_sel_hi:[0,1,1]
	v_pk_fma_f32 v[90:91], v[122:123], v[134:135], v[90:91] op_sel:[1,0,0]
	s_waitcnt lgkmcnt(0)
	v_pk_mul_f32 v[134:135], v[28:29], v[24:25] op_sel_hi:[1,0]
	v_pk_mul_f32 v[116:117], v[28:29], v[130:131] op_sel_hi:[1,0]
	v_pk_fma_f32 v[134:135], v[34:35], v[24:25], v[134:135] op_sel:[0,1,0]
	v_pk_fma_f32 v[116:117], v[34:35], v[130:131], v[116:117] op_sel:[0,1,0]
	v_pk_fma_f32 v[134:135], v[32:33], v[26:27], v[134:135] op_sel_hi:[1,0,1]
	v_pk_fma_f32 v[116:117], v[32:33], v[132:133], v[116:117] op_sel_hi:[1,0,1]
	v_pk_fma_f32 v[134:135], v[90:91], v[26:27], v[134:135] op_sel:[0,1,0]
	v_pk_fma_f32 v[116:117], v[90:91], v[132:133], v[116:117] op_sel:[0,1,0]
	v_cvt_pk_f16_f32 v116, v116, v117
	v_add_f32_dpp v134, v134, v134 quad_perm:[1,0,3,2] row_mask:0xf bank_mask:0xf bound_ctrl:1
	v_add_f32_dpp v135, v135, v135 quad_perm:[1,0,3,2] row_mask:0xf bank_mask:0xf bound_ctrl:1
	ds_write_b32 v42, v116 offset:13312
	v_pk_fma_f32 v[28:29], v[20:21], v[30:31], v[28:29] op_sel_hi:[0,1,1]
	v_add_f32_dpp v134, v134, v134 quad_perm:[2,3,0,1] row_mask:0xf bank_mask:0xf bound_ctrl:1
	v_add_f32_dpp v135, v135, v135 quad_perm:[2,3,0,1] row_mask:0xf bank_mask:0xf bound_ctrl:1
	v_pk_fma_f32 v[34:35], v[20:21], v[30:31], v[34:35] op_sel:[1,0,0]
	v_add_f32_dpp v134, v134, v134 row_half_mirror row_mask:0xf bank_mask:0xf bound_ctrl:1
	v_add_f32_dpp v135, v135, v135 row_half_mirror row_mask:0xf bank_mask:0xf bound_ctrl:1
	v_pk_fma_f32 v[32:33], v[22:23], v[30:31], v[32:33] op_sel_hi:[0,1,1]
	v_pk_fma_f32 v[90:91], v[22:23], v[30:31], v[90:91] op_sel:[1,0,0]
	ds_read_b64 v[30:31], v95 offset:22272
	ds_read_b128 v[116:119], v93 offset:15872
	ds_read_b128 v[120:123], v93 offset:19968
	ds_read_b128 v[124:127], v93 offset:11776
	ds_read_b128 v[130:133], v93 offset:3584
	ds_read_b64 v[96:97], v92 offset:1792
	v_add_f32_dpp v134, v134, v134 row_mirror row_mask:0xf bank_mask:0xf bound_ctrl:1
	v_add_f32_dpp v135, v135, v135 row_mirror row_mask:0xf bank_mask:0xf bound_ctrl:1
	v_pk_fma_f32 v[28:29], v[16:17], v[134:135], v[28:29] op_sel_hi:[0,1,1]
	v_pk_fma_f32 v[34:35], v[16:17], v[134:135], v[34:35] op_sel:[1,0,0]
	v_pk_fma_f32 v[32:33], v[18:19], v[134:135], v[32:33] op_sel_hi:[0,1,1]
	v_pk_fma_f32 v[90:91], v[18:19], v[134:135], v[90:91] op_sel:[1,0,0]
	s_waitcnt lgkmcnt(4)
	v_pk_mul_f32 v[134:135], v[28:29], v[116:117] op_sel_hi:[1,0]
	v_pk_mul_f32 v[16:17], v[28:29], v[12:13] op_sel_hi:[1,0]
	v_pk_fma_f32 v[134:135], v[34:35], v[116:117], v[134:135] op_sel:[0,1,0]
	v_pk_fma_f32 v[16:17], v[34:35], v[12:13], v[16:17] op_sel:[0,1,0]
	v_pk_fma_f32 v[134:135], v[32:33], v[118:119], v[134:135] op_sel_hi:[1,0,1]
	v_pk_fma_f32 v[16:17], v[32:33], v[14:15], v[16:17] op_sel_hi:[1,0,1]
	v_pk_fma_f32 v[134:135], v[90:91], v[118:119], v[134:135] op_sel:[0,1,0]
	v_pk_fma_f32 v[16:17], v[90:91], v[14:15], v[16:17] op_sel:[0,1,0]
	v_cvt_pk_f16_f32 v16, v16, v17
	v_add_f32_dpp v134, v134, v134 quad_perm:[1,0,3,2] row_mask:0xf bank_mask:0xf bound_ctrl:1
	v_add_f32_dpp v135, v135, v135 quad_perm:[1,0,3,2] row_mask:0xf bank_mask:0xf bound_ctrl:1
	ds_write_b32 v42, v16 offset:14336
	ds_read_b128 v[24:27], v94 offset:15872
	ds_read_b128 v[16:19], v94 offset:19968
	ds_read_b128 v[20:23], v94 offset:11776
	ds_read_b128 v[12:15], v94 offset:3584
	s_waitcnt lgkmcnt(5)
	v_pk_fma_f32 v[28:29], v[124:125], v[96:97], v[28:29] op_sel_hi:[0,1,1]
	v_add_f32_dpp v134, v134, v134 quad_perm:[2,3,0,1] row_mask:0xf bank_mask:0xf bound_ctrl:1
	v_add_f32_dpp v135, v135, v135 quad_perm:[2,3,0,1] row_mask:0xf bank_mask:0xf bound_ctrl:1
	v_pk_fma_f32 v[34:35], v[124:125], v[96:97], v[34:35] op_sel:[1,0,0]
	v_add_f32_dpp v134, v134, v134 row_half_mirror row_mask:0xf bank_mask:0xf bound_ctrl:1
	v_add_f32_dpp v135, v135, v135 row_half_mirror row_mask:0xf bank_mask:0xf bound_ctrl:1
	v_pk_fma_f32 v[32:33], v[126:127], v[96:97], v[32:33] op_sel_hi:[0,1,1]
	v_pk_fma_f32 v[90:91], v[126:127], v[96:97], v[90:91] op_sel:[1,0,0]
	v_add_f32_dpp v134, v134, v134 row_mirror row_mask:0xf bank_mask:0xf bound_ctrl:1
	v_add_f32_dpp v135, v135, v135 row_mirror row_mask:0xf bank_mask:0xf bound_ctrl:1
	v_pk_fma_f32 v[28:29], v[120:121], v[134:135], v[28:29] op_sel_hi:[0,1,1]
	v_pk_fma_f32 v[34:35], v[120:121], v[134:135], v[34:35] op_sel:[1,0,0]
	v_pk_fma_f32 v[32:33], v[122:123], v[134:135], v[32:33] op_sel_hi:[0,1,1]
	v_pk_fma_f32 v[90:91], v[122:123], v[134:135], v[90:91] op_sel:[1,0,0]
	v_pk_mul_f32 v[116:117], v[28:29], v[130:131] op_sel_hi:[1,0]
	v_pk_fma_f32 v[116:117], v[34:35], v[130:131], v[116:117] op_sel:[0,1,0]
	v_pk_fma_f32 v[116:117], v[32:33], v[132:133], v[116:117] op_sel_hi:[1,0,1]
	v_pk_fma_f32 v[116:117], v[90:91], v[132:133], v[116:117] op_sel:[0,1,0]
	v_cvt_pk_f16_f32 v116, v116, v117
	ds_write_b32 v42, v116 offset:15360
	v_swap_b32 v29, v34
	v_swap_b32 v33, v90
	s_waitcnt vmcnt(4) lgkmcnt(1)
	v_cvt_f32_f16_sdwa v31, v72 dst_sel:DWORD dst_unused:UNUSED_PAD src0_sel:WORD_1
	v_cvt_f32_f16_e32 v30, v72
	v_cvt_f32_f16_sdwa v93, v73 dst_sel:DWORD dst_unused:UNUSED_PAD src0_sel:WORD_1
	v_cvt_f32_f16_e32 v92, v73
	s_waitcnt vmcnt(1)
	v_cvt_f32_f16_sdwa v17, v80 dst_sel:DWORD dst_unused:UNUSED_PAD src0_sel:WORD_1
	v_cvt_f32_f16_e32 v16, v80
	v_cvt_f32_f16_sdwa v19, v81 dst_sel:DWORD dst_unused:UNUSED_PAD src0_sel:WORD_1
	v_cvt_f32_f16_e32 v18, v81
	v_pk_mul_f32 v[22:23], v[0:1], v[30:31]
	v_pk_mul_f32 v[20:21], v[2:3], v[92:93]
	v_pk_mul_f32 v[96:97], v[22:23], v[22:23]
	ds_read_b128 v[12:15], v94 offset:7936
	v_pk_mul_f32 v[94:95], v[20:21], v[20:21]
	v_add_f32_e32 v42, v96, v97
	v_cvt_f32_f16_sdwa v25, v70 dst_sel:DWORD dst_unused:UNUSED_PAD src0_sel:WORD_1
	v_cvt_f32_f16_e32 v24, v70
	v_cvt_f32_f16_sdwa v27, v71 dst_sel:DWORD dst_unused:UNUSED_PAD src0_sel:WORD_1
	v_cvt_f32_f16_e32 v26, v71
	v_add_f32_e32 v42, v94, v42
	v_add_f32_e32 v42, v95, v42
	v_pk_add_f32 v[94:95], v[16:17], -1.0 op_sel_hi:[1,0]
	v_pk_add_f32 v[96:97], v[18:19], -1.0 op_sel_hi:[1,0]
	v_pk_fma_f32 v[94:95], v[4:5], v[94:95], 1.0 op_sel_hi:[1,1,0]
	v_pk_fma_f32 v[96:97], v[6:7], v[96:97], 1.0 op_sel_hi:[1,1,0]
	v_pk_mul_f32 v[94:95], v[30:31], v[94:95]
	v_pk_mul_f32 v[96:97], v[92:93], v[96:97]
	v_pk_mul_f32 v[30:31], v[24:25], v[94:95]
	v_pk_mul_f32 v[92:93], v[26:27], v[96:97]
	v_pk_mul_f32 v[30:31], v[8:9], v[30:31]
	v_pk_mul_f32 v[92:93], v[10:11], v[92:93]
	v_add_f32_e32 v30, v30, v31
	v_add_f32_e32 v31, v92, v93
	v_add_f32_e32 v30, v30, v31
	v_add_f32_dpp v42, v42, v42 quad_perm:[1,0,3,2] row_mask:0xf bank_mask:0xf bound_ctrl:1
	s_nop 0
	v_add_f32_dpp v30, v30, v30 quad_perm:[1,0,3,2] row_mask:0xf bank_mask:0xf bound_ctrl:1
	v_add_f32_dpp v42, v42, v42 quad_perm:[2,3,0,1] row_mask:0xf bank_mask:0xf bound_ctrl:1
	s_nop 0
	v_add_f32_dpp v30, v30, v30 quad_perm:[2,3,0,1] row_mask:0xf bank_mask:0xf bound_ctrl:1
	v_add_f32_dpp v42, v42, v42 row_half_mirror row_mask:0xf bank_mask:0xf bound_ctrl:1
	s_nop 0
	v_add_f32_dpp v30, v30, v30 row_half_mirror row_mask:0xf bank_mask:0xf bound_ctrl:1
	v_mov_b32_dpp v116, v42 row_mirror row_mask:0xf bank_mask:0xf bound_ctrl:1
	s_nop 0
	v_mov_b32_dpp v31, v30 row_mirror row_mask:0xf bank_mask:0xf bound_ctrl:1
	s_and_saveexec_b64 s[12:13], s[6:7]
	s_cbranch_execz .LBB0_430
	s_add_i32 s42, s95, 16
	v_cmp_lt_u32_e32 vcc, s42, v106
	s_and_b64 exec, exec, vcc
	s_cbranch_execz .LBB0_430
	v_add_f32_e32 v92, v30, v31
	v_add_u32_e32 v30, s42, v46
	v_ashrrev_i32_e32 v31, 31, v30
	v_lshlrev_b64 v[30:31], 6, v[30:31]
	v_lshl_add_u64 v[30:31], s[58:59], 0, v[30:31]
	global_store_dword v[30:31], v92, off

.LBB0_437:
	v_swap_b32 v93, v94
	v_swap_b32 v33, v34
	s_waitcnt lgkmcnt(0)
	v_pk_mul_f32 v[130:131], v[92:93], v[24:25] op_sel_hi:[1,0]
	v_pk_fma_f32 v[130:131], v[94:95], v[24:25], v[130:131] op_sel:[0,1,0]
	v_pk_fma_f32 v[130:131], v[32:33], v[26:27], v[130:131] op_sel_hi:[1,0,1]
	v_pk_fma_f32 v[130:131], v[34:35], v[26:27], v[130:131] op_sel:[0,1,0]
	v_pk_fma_f32 v[92:93], v[28:29], v[96:97], v[92:93] op_sel_hi:[0,1,1]
	v_pk_fma_f32 v[94:95], v[28:29], v[96:97], v[94:95] op_sel:[1,0,0]
	v_add_f32_dpp v130, v130, v130 quad_perm:[1,0,3,2] row_mask:0xf bank_mask:0xf bound_ctrl:1
	v_add_f32_dpp v131, v131, v131 quad_perm:[1,0,3,2] row_mask:0xf bank_mask:0xf bound_ctrl:1
	v_pk_fma_f32 v[32:33], v[30:31], v[96:97], v[32:33] op_sel_hi:[0,1,1]
	v_add_f32_dpp v130, v130, v130 quad_perm:[2,3,0,1] row_mask:0xf bank_mask:0xf bound_ctrl:1
	v_add_f32_dpp v131, v131, v131 quad_perm:[2,3,0,1] row_mask:0xf bank_mask:0xf bound_ctrl:1
	v_pk_fma_f32 v[34:35], v[30:31], v[96:97], v[34:35] op_sel:[1,0,0]
	v_add_f32_dpp v130, v130, v130 row_half_mirror row_mask:0xf bank_mask:0xf bound_ctrl:1
	v_add_f32_dpp v131, v131, v131 row_half_mirror row_mask:0xf bank_mask:0xf bound_ctrl:1
	ds_read_b64 v[96:97], v115 offset:20736
	ds_read_b128 v[12:15], v113 offset:12288
	ds_read_b128 v[116:119], v113 offset:16384
	ds_read_b128 v[120:123], v113 offset:8192
	ds_read_b128 v[124:127], v113
	ds_read_b64 v[90:91], v112
	v_add_f32_dpp v130, v130, v130 row_mirror row_mask:0xf bank_mask:0xf bound_ctrl:1
	v_add_f32_dpp v131, v131, v131 row_mirror row_mask:0xf bank_mask:0xf bound_ctrl:1
	v_pk_fma_f32 v[92:93], v[20:21], v[130:131], v[92:93] op_sel_hi:[0,1,1]
	v_pk_fma_f32 v[94:95], v[20:21], v[130:131], v[94:95] op_sel:[1,0,0]
	v_pk_fma_f32 v[32:33], v[22:23], v[130:131], v[32:33] op_sel_hi:[0,1,1]
	v_pk_fma_f32 v[34:35], v[22:23], v[130:131], v[34:35] op_sel:[1,0,0]
	s_waitcnt lgkmcnt(4)
	v_pk_mul_f32 v[130:131], v[92:93], v[12:13] op_sel_hi:[1,0]
	v_pk_mul_f32 v[20:21], v[92:93], v[16:17] op_sel_hi:[1,0]
	v_pk_fma_f32 v[130:131], v[94:95], v[12:13], v[130:131] op_sel:[0,1,0]
	v_pk_fma_f32 v[20:21], v[94:95], v[16:17], v[20:21] op_sel:[0,1,0]
	v_pk_fma_f32 v[130:131], v[32:33], v[14:15], v[130:131] op_sel_hi:[1,0,1]
	v_pk_fma_f32 v[20:21], v[32:33], v[18:19], v[20:21] op_sel_hi:[1,0,1]
	v_pk_fma_f32 v[130:131], v[34:35], v[14:15], v[130:131] op_sel:[0,1,0]
	v_pk_fma_f32 v[20:21], v[34:35], v[18:19], v[20:21] op_sel:[0,1,0]
	v_cvt_pk_f16_f32 v20, v20, v21
	v_add_f32_dpp v130, v130, v130 quad_perm:[1,0,3,2] row_mask:0xf bank_mask:0xf bound_ctrl:1
	v_add_f32_dpp v131, v131, v131 quad_perm:[1,0,3,2] row_mask:0xf bank_mask:0xf bound_ctrl:1
	ds_write_b32 v47, v20
	ds_read_b128 v[24:27], v114 offset:12800
	ds_read_b128 v[20:23], v114 offset:16896
	ds_read_b128 v[28:31], v114 offset:8704
	ds_read_b128 v[16:19], v114 offset:512
	s_waitcnt lgkmcnt(5)
	v_pk_fma_f32 v[92:93], v[120:121], v[90:91], v[92:93] op_sel_hi:[0,1,1]
	v_add_f32_dpp v130, v130, v130 quad_perm:[2,3,0,1] row_mask:0xf bank_mask:0xf bound_ctrl:1
	v_add_f32_dpp v131, v131, v131 quad_perm:[2,3,0,1] row_mask:0xf bank_mask:0xf bound_ctrl:1
	v_pk_fma_f32 v[94:95], v[120:121], v[90:91], v[94:95] op_sel:[1,0,0]
	v_add_f32_dpp v130, v130, v130 row_half_mirror row_mask:0xf bank_mask:0xf bound_ctrl:1
	v_add_f32_dpp v131, v131, v131 row_half_mirror row_mask:0xf bank_mask:0xf bound_ctrl:1
	v_pk_fma_f32 v[32:33], v[122:123], v[90:91], v[32:33] op_sel_hi:[0,1,1]
	v_pk_fma_f32 v[34:35], v[122:123], v[90:91], v[34:35] op_sel:[1,0,0]
	v_add_f32_dpp v130, v130, v130 row_mirror row_mask:0xf bank_mask:0xf bound_ctrl:1
	v_add_f32_dpp v131, v131, v131 row_mirror row_mask:0xf bank_mask:0xf bound_ctrl:1
	v_pk_fma_f32 v[92:93], v[116:117], v[130:131], v[92:93] op_sel_hi:[0,1,1]
	v_pk_fma_f32 v[94:95], v[116:117], v[130:131], v[94:95] op_sel:[1,0,0]
	v_pk_fma_f32 v[32:33], v[118:119], v[130:131], v[32:33] op_sel_hi:[0,1,1]
	v_pk_fma_f32 v[34:35], v[118:119], v[130:131], v[34:35] op_sel:[1,0,0]
	s_waitcnt lgkmcnt(0)
	v_pk_mul_f32 v[130:131], v[92:93], v[24:25] op_sel_hi:[1,0]
	v_pk_mul_f32 v[12:13], v[92:93], v[124:125] op_sel_hi:[1,0]
	v_pk_fma_f32 v[130:131], v[94:95], v[24:25], v[130:131] op_sel:[0,1,0]
	v_pk_fma_f32 v[12:13], v[94:95], v[124:125], v[12:13] op_sel:[0,1,0]
	v_pk_fma_f32 v[130:131], v[32:33], v[26:27], v[130:131] op_sel_hi:[1,0,1]
	v_pk_fma_f32 v[12:13], v[32:33], v[126:127], v[12:13] op_sel_hi:[1,0,1]
	v_pk_fma_f32 v[130:131], v[34:35], v[26:27], v[130:131] op_sel:[0,1,0]
	v_pk_fma_f32 v[12:13], v[34:35], v[126:127], v[12:13] op_sel:[0,1,0]
	v_cvt_pk_f16_f32 v12, v12, v13
	v_add_f32_dpp v130, v130, v130 quad_perm:[1,0,3,2] row_mask:0xf bank_mask:0xf bound_ctrl:1
	v_add_f32_dpp v131, v131, v131 quad_perm:[1,0,3,2] row_mask:0xf bank_mask:0xf bound_ctrl:1
	ds_write_b32 v47, v12 offset:1024
	v_pk_fma_f32 v[92:93], v[28:29], v[96:97], v[92:93] op_sel_hi:[0,1,1]
	v_add_f32_dpp v130, v130, v130 quad_perm:[2,3,0,1] row_mask:0xf bank_mask:0xf bound_ctrl:1
	v_add_f32_dpp v131, v131, v131 quad_perm:[2,3,0,1] row_mask:0xf bank_mask:0xf bound_ctrl:1
	v_pk_fma_f32 v[94:95], v[28:29], v[96:97], v[94:95] op_sel:[1,0,0]
	v_add_f32_dpp v130, v130, v130 row_half_mirror row_mask:0xf bank_mask:0xf bound_ctrl:1
	v_add_f32_dpp v131, v131, v131 row_half_mirror row_mask:0xf bank_mask:0xf bound_ctrl:1
	v_pk_fma_f32 v[32:33], v[30:31], v[96:97], v[32:33] op_sel_hi:[0,1,1]
	v_pk_fma_f32 v[34:35], v[30:31], v[96:97], v[34:35] op_sel:[1,0,0]
	ds_read_b64 v[96:97], v115 offset:20992
	ds_read_b128 v[12:15], v113 offset:12800
	ds_read_b128 v[116:119], v113 offset:16896
	ds_read_b128 v[120:123], v113 offset:8704
	ds_read_b128 v[124:127], v113 offset:512
	ds_read_b64 v[90:91], v112 offset:256
	v_add_f32_dpp v130, v130, v130 row_mirror row_mask:0xf bank_mask:0xf bound_ctrl:1
	v_add_f32_dpp v131, v131, v131 row_mirror row_mask:0xf bank_mask:0xf bound_ctrl:1
	v_pk_fma_f32 v[92:93], v[20:21], v[130:131], v[92:93] op_sel_hi:[0,1,1]
	v_pk_fma_f32 v[94:95], v[20:21], v[130:131], v[94:95] op_sel:[1,0,0]
	v_pk_fma_f32 v[32:33], v[22:23], v[130:131], v[32:33] op_sel_hi:[0,1,1]
	v_pk_fma_f32 v[34:35], v[22:23], v[130:131], v[34:35] op_sel:[1,0,0]
	s_waitcnt lgkmcnt(4)
	v_pk_mul_f32 v[130:131], v[92:93], v[12:13] op_sel_hi:[1,0]
	v_pk_mul_f32 v[20:21], v[92:93], v[16:17] op_sel_hi:[1,0]
	v_pk_fma_f32 v[130:131], v[94:95], v[12:13], v[130:131] op_sel:[0,1,0]
	v_pk_fma_f32 v[20:21], v[94:95], v[16:17], v[20:21] op_sel:[0,1,0]
	v_pk_fma_f32 v[130:131], v[32:33], v[14:15], v[130:131] op_sel_hi:[1,0,1]
	v_pk_fma_f32 v[20:21], v[32:33], v[18:19], v[20:21] op_sel_hi:[1,0,1]
	v_pk_fma_f32 v[130:131], v[34:35], v[14:15], v[130:131] op_sel:[0,1,0]
	v_pk_fma_f32 v[20:21], v[34:35], v[18:19], v[20:21] op_sel:[0,1,0]
	v_cvt_pk_f16_f32 v20, v20, v21
	v_add_f32_dpp v130, v130, v130 quad_perm:[1,0,3,2] row_mask:0xf bank_mask:0xf bound_ctrl:1
	v_add_f32_dpp v131, v131, v131 quad_perm:[1,0,3,2] row_mask:0xf bank_mask:0xf bound_ctrl:1
	ds_write_b32 v47, v20 offset:2048
	ds_read_b128 v[24:27], v114 offset:13312
	ds_read_b128 v[20:23], v114 offset:17408
	ds_read_b128 v[28:31], v114 offset:9216
	ds_read_b128 v[16:19], v114 offset:1024
	s_waitcnt lgkmcnt(5)
	v_pk_fma_f32 v[92:93], v[120:121], v[90:91], v[92:93] op_sel_hi:[0,1,1]
	v_add_f32_dpp v130, v130, v130 quad_perm:[2,3,0,1] row_mask:0xf bank_mask:0xf bound_ctrl:1
	v_add_f32_dpp v131, v131, v131 quad_perm:[2,3,0,1] row_mask:0xf bank_mask:0xf bound_ctrl:1
	v_pk_fma_f32 v[94:95], v[120:121], v[90:91], v[94:95] op_sel:[1,0,0]
	v_add_f32_dpp v130, v130, v130 row_half_mirror row_mask:0xf bank_mask:0xf bound_ctrl:1
	v_add_f32_dpp v131, v131, v131 row_half_mirror row_mask:0xf bank_mask:0xf bound_ctrl:1
	v_pk_fma_f32 v[32:33], v[122:123], v[90:91], v[32:33] op_sel_hi:[0,1,1]
	v_pk_fma_f32 v[34:35], v[122:123], v[90:91], v[34:35] op_sel:[1,0,0]
	v_add_f32_dpp v130, v130, v130 row_mirror row_mask:0xf bank_mask:0xf bound_ctrl:1
	v_add_f32_dpp v131, v131, v131 row_mirror row_mask:0xf bank_mask:0xf bound_ctrl:1
	v_pk_fma_f32 v[92:93], v[116:117], v[130:131], v[92:93] op_sel_hi:[0,1,1]
	v_pk_fma_f32 v[94:95], v[116:117], v[130:131], v[94:95] op_sel:[1,0,0]
	v_pk_fma_f32 v[32:33], v[118:119], v[130:131], v[32:33] op_sel_hi:[0,1,1]
	v_pk_fma_f32 v[34:35], v[118:119], v[130:131], v[34:35] op_sel:[1,0,0]
	s_waitcnt lgkmcnt(0)
	v_pk_mul_f32 v[130:131], v[92:93], v[24:25] op_sel_hi:[1,0]
	v_pk_mul_f32 v[12:13], v[92:93], v[124:125] op_sel_hi:[1,0]
	v_pk_fma_f32 v[130:131], v[94:95], v[24:25], v[130:131] op_sel:[0,1,0]
	v_pk_fma_f32 v[12:13], v[94:95], v[124:125], v[12:13] op_sel:[0,1,0]
	v_pk_fma_f32 v[130:131], v[32:33], v[26:27], v[130:131] op_sel_hi:[1,0,1]
	v_pk_fma_f32 v[12:13], v[32:33], v[126:127], v[12:13] op_sel_hi:[1,0,1]
	v_pk_fma_f32 v[130:131], v[34:35], v[26:27], v[130:131] op_sel:[0,1,0]
	v_pk_fma_f32 v[12:13], v[34:35], v[126:127], v[12:13] op_sel:[0,1,0]
	v_cvt_pk_f16_f32 v12, v12, v13
	v_add_f32_dpp v130, v130, v130 quad_perm:[1,0,3,2] row_mask:0xf bank_mask:0xf bound_ctrl:1
	v_add_f32_dpp v131, v131, v131 quad_perm:[1,0,3,2] row_mask:0xf bank_mask:0xf bound_ctrl:1
	ds_write_b32 v47, v12 offset:3072
	v_pk_fma_f32 v[92:93], v[28:29], v[96:97], v[92:93] op_sel_hi:[0,1,1]
	v_add_f32_dpp v130, v130, v130 quad_perm:[2,3,0,1] row_mask:0xf bank_mask:0xf bound_ctrl:1
	v_add_f32_dpp v131, v131, v131 quad_perm:[2,3,0,1] row_mask:0xf bank_mask:0xf bound_ctrl:1
	v_pk_fma_f32 v[94:95], v[28:29], v[96:97], v[94:95] op_sel:[1,0,0]
	v_add_f32_dpp v130, v130, v130 row_half_mirror row_mask:0xf bank_mask:0xf bound_ctrl:1
	v_add_f32_dpp v131, v131, v131 row_half_mirror row_mask:0xf bank_mask:0xf bound_ctrl:1
	v_pk_fma_f32 v[32:33], v[30:31], v[96:97], v[32:33] op_sel_hi:[0,1,1]
	v_pk_fma_f32 v[34:35], v[30:31], v[96:97], v[34:35] op_sel:[1,0,0]
	ds_read_b64 v[96:97], v115 offset:21248
	ds_read_b128 v[12:15], v113 offset:13312
	ds_read_b128 v[116:119], v113 offset:17408
	ds_read_b128 v[120:123], v113 offset:9216
	ds_read_b128 v[124:127], v113 offset:1024
	ds_read_b64 v[90:91], v112 offset:512
	v_add_f32_dpp v130, v130, v130 row_mirror row_mask:0xf bank_mask:0xf bound_ctrl:1
	v_add_f32_dpp v131, v131, v131 row_mirror row_mask:0xf bank_mask:0xf bound_ctrl:1
	v_pk_fma_f32 v[92:93], v[20:21], v[130:131], v[92:93] op_sel_hi:[0,1,1]
	v_pk_fma_f32 v[94:95], v[20:21], v[130:131], v[94:95] op_sel:[1,0,0]
	v_pk_fma_f32 v[32:33], v[22:23], v[130:131], v[32:33] op_sel_hi:[0,1,1]
	v_pk_fma_f32 v[34:35], v[22:23], v[130:131], v[34:35] op_sel:[1,0,0]
	s_waitcnt lgkmcnt(4)
	v_pk_mul_f32 v[130:131], v[92:93], v[12:13] op_sel_hi:[1,0]
	v_pk_mul_f32 v[20:21], v[92:93], v[16:17] op_sel_hi:[1,0]
	v_pk_fma_f32 v[130:131], v[94:95], v[12:13], v[130:131] op_sel:[0,1,0]
	v_pk_fma_f32 v[20:21], v[94:95], v[16:17], v[20:21] op_sel:[0,1,0]
	v_pk_fma_f32 v[130:131], v[32:33], v[14:15], v[130:131] op_sel_hi:[1,0,1]
	v_pk_fma_f32 v[20:21], v[32:33], v[18:19], v[20:21] op_sel_hi:[1,0,1]
	v_pk_fma_f32 v[130:131], v[34:35], v[14:15], v[130:131] op_sel:[0,1,0]
	v_pk_fma_f32 v[20:21], v[34:35], v[18:19], v[20:21] op_sel:[0,1,0]
	v_cvt_pk_f16_f32 v20, v20, v21
	v_add_f32_dpp v130, v130, v130 quad_perm:[1,0,3,2] row_mask:0xf bank_mask:0xf bound_ctrl:1
	v_add_f32_dpp v131, v131, v131 quad_perm:[1,0,3,2] row_mask:0xf bank_mask:0xf bound_ctrl:1
	ds_write_b32 v47, v20 offset:4096
	ds_read_b128 v[24:27], v114 offset:13824
	ds_read_b128 v[20:23], v114 offset:17920
	ds_read_b128 v[28:31], v114 offset:9728
	ds_read_b128 v[16:19], v114 offset:1536
	s_waitcnt lgkmcnt(5)
	v_pk_fma_f32 v[92:93], v[120:121], v[90:91], v[92:93] op_sel_hi:[0,1,1]
	v_add_f32_dpp v130, v130, v130 quad_perm:[2,3,0,1] row_mask:0xf bank_mask:0xf bound_ctrl:1
	v_add_f32_dpp v131, v131, v131 quad_perm:[2,3,0,1] row_mask:0xf bank_mask:0xf bound_ctrl:1
	v_pk_fma_f32 v[94:95], v[120:121], v[90:91], v[94:95] op_sel:[1,0,0]
	v_add_f32_dpp v130, v130, v130 row_half_mirror row_mask:0xf bank_mask:0xf bound_ctrl:1
	v_add_f32_dpp v131, v131, v131 row_half_mirror row_mask:0xf bank_mask:0xf bound_ctrl:1
	v_pk_fma_f32 v[32:33], v[122:123], v[90:91], v[32:33] op_sel_hi:[0,1,1]
	v_pk_fma_f32 v[34:35], v[122:123], v[90:91], v[34:35] op_sel:[1,0,0]
	v_add_f32_dpp v130, v130, v130 row_mirror row_mask:0xf bank_mask:0xf bound_ctrl:1
	v_add_f32_dpp v131, v131, v131 row_mirror row_mask:0xf bank_mask:0xf bound_ctrl:1
	v_pk_fma_f32 v[92:93], v[116:117], v[130:131], v[92:93] op_sel_hi:[0,1,1]
	v_pk_fma_f32 v[94:95], v[116:117], v[130:131], v[94:95] op_sel:[1,0,0]
	v_pk_fma_f32 v[32:33], v[118:119], v[130:131], v[32:33] op_sel_hi:[0,1,1]
	v_pk_fma_f32 v[34:35], v[118:119], v[130:131], v[34:35] op_sel:[1,0,0]
	s_waitcnt lgkmcnt(0)
	v_pk_mul_f32 v[130:131], v[92:93], v[24:25] op_sel_hi:[1,0]
	v_pk_mul_f32 v[12:13], v[92:93], v[124:125] op_sel_hi:[1,0]
	v_pk_fma_f32 v[130:131], v[94:95], v[24:25], v[130:131] op_sel:[0,1,0]
	v_pk_fma_f32 v[12:13], v[94:95], v[124:125], v[12:13] op_sel:[0,1,0]
	v_pk_fma_f32 v[130:131], v[32:33], v[26:27], v[130:131] op_sel_hi:[1,0,1]
	v_pk_fma_f32 v[12:13], v[32:33], v[126:127], v[12:13] op_sel_hi:[1,0,1]
	v_pk_fma_f32 v[130:131], v[34:35], v[26:27], v[130:131] op_sel:[0,1,0]
	v_pk_fma_f32 v[12:13], v[34:35], v[126:127], v[12:13] op_sel:[0,1,0]
	v_cvt_pk_f16_f32 v12, v12, v13
	v_add_f32_dpp v130, v130, v130 quad_perm:[1,0,3,2] row_mask:0xf bank_mask:0xf bound_ctrl:1
	v_add_f32_dpp v131, v131, v131 quad_perm:[1,0,3,2] row_mask:0xf bank_mask:0xf bound_ctrl:1
	ds_write_b32 v47, v12 offset:5120
	v_pk_fma_f32 v[92:93], v[28:29], v[96:97], v[92:93] op_sel_hi:[0,1,1]
	v_add_f32_dpp v130, v130, v130 quad_perm:[2,3,0,1] row_mask:0xf bank_mask:0xf bound_ctrl:1
	v_add_f32_dpp v131, v131, v131 quad_perm:[2,3,0,1] row_mask:0xf bank_mask:0xf bound_ctrl:1
	v_pk_fma_f32 v[94:95], v[28:29], v[96:97], v[94:95] op_sel:[1,0,0]
	v_add_f32_dpp v130, v130, v130 row_half_mirror row_mask:0xf bank_mask:0xf bound_ctrl:1
	v_add_f32_dpp v131, v131, v131 row_half_mirror row_mask:0xf bank_mask:0xf bound_ctrl:1
	v_pk_fma_f32 v[32:33], v[30:31], v[96:97], v[32:33] op_sel_hi:[0,1,1]
	v_pk_fma_f32 v[34:35], v[30:31], v[96:97], v[34:35] op_sel:[1,0,0]
	ds_read_b64 v[96:97], v115 offset:21504
	ds_read_b128 v[12:15], v113 offset:13824
	ds_read_b128 v[116:119], v113 offset:17920
	ds_read_b128 v[120:123], v113 offset:9728
	ds_read_b128 v[124:127], v113 offset:1536
	ds_read_b64 v[90:91], v112 offset:768
	v_add_f32_dpp v130, v130, v130 row_mirror row_mask:0xf bank_mask:0xf bound_ctrl:1
	v_add_f32_dpp v131, v131, v131 row_mirror row_mask:0xf bank_mask:0xf bound_ctrl:1
	v_pk_fma_f32 v[92:93], v[20:21], v[130:131], v[92:93] op_sel_hi:[0,1,1]
	v_pk_fma_f32 v[94:95], v[20:21], v[130:131], v[94:95] op_sel:[1,0,0]
	v_pk_fma_f32 v[32:33], v[22:23], v[130:131], v[32:33] op_sel_hi:[0,1,1]
	v_pk_fma_f32 v[34:35], v[22:23], v[130:131], v[34:35] op_sel:[1,0,0]
	s_waitcnt lgkmcnt(4)
	v_pk_mul_f32 v[130:131], v[92:93], v[12:13] op_sel_hi:[1,0]
	v_pk_mul_f32 v[20:21], v[92:93], v[16:17] op_sel_hi:[1,0]
	v_pk_fma_f32 v[130:131], v[94:95], v[12:13], v[130:131] op_sel:[0,1,0]
	v_pk_fma_f32 v[20:21], v[94:95], v[16:17], v[20:21] op_sel:[0,1,0]
	v_pk_fma_f32 v[130:131], v[32:33], v[14:15], v[130:131] op_sel_hi:[1,0,1]
	v_pk_fma_f32 v[20:21], v[32:33], v[18:19], v[20:21] op_sel_hi:[1,0,1]
	v_pk_fma_f32 v[130:131], v[34:35], v[14:15], v[130:131] op_sel:[0,1,0]
	v_pk_fma_f32 v[20:21], v[34:35], v[18:19], v[20:21] op_sel:[0,1,0]
	v_cvt_pk_f16_f32 v20, v20, v21
	v_add_f32_dpp v130, v130, v130 quad_perm:[1,0,3,2] row_mask:0xf bank_mask:0xf bound_ctrl:1
	v_add_f32_dpp v131, v131, v131 quad_perm:[1,0,3,2] row_mask:0xf bank_mask:0xf bound_ctrl:1
	ds_write_b32 v47, v20 offset:6144
	ds_read_b128 v[24:27], v114 offset:14336
	ds_read_b128 v[20:23], v114 offset:18432
	ds_read_b128 v[28:31], v114 offset:10240
	ds_read_b128 v[16:19], v114 offset:2048
	s_waitcnt lgkmcnt(5)
	v_pk_fma_f32 v[92:93], v[120:121], v[90:91], v[92:93] op_sel_hi:[0,1,1]
	v_add_f32_dpp v130, v130, v130 quad_perm:[2,3,0,1] row_mask:0xf bank_mask:0xf bound_ctrl:1
	v_add_f32_dpp v131, v131, v131 quad_perm:[2,3,0,1] row_mask:0xf bank_mask:0xf bound_ctrl:1
	v_pk_fma_f32 v[94:95], v[120:121], v[90:91], v[94:95] op_sel:[1,0,0]
	v_add_f32_dpp v130, v130, v130 row_half_mirror row_mask:0xf bank_mask:0xf bound_ctrl:1
	v_add_f32_dpp v131, v131, v131 row_half_mirror row_mask:0xf bank_mask:0xf bound_ctrl:1
	v_pk_fma_f32 v[32:33], v[122:123], v[90:91], v[32:33] op_sel_hi:[0,1,1]
	v_pk_fma_f32 v[34:35], v[122:123], v[90:91], v[34:35] op_sel:[1,0,0]
	v_add_f32_dpp v130, v130, v130 row_mirror row_mask:0xf bank_mask:0xf bound_ctrl:1
	v_add_f32_dpp v131, v131, v131 row_mirror row_mask:0xf bank_mask:0xf bound_ctrl:1
	v_pk_fma_f32 v[92:93], v[116:117], v[130:131], v[92:93] op_sel_hi:[0,1,1]
	v_pk_fma_f32 v[94:95], v[116:117], v[130:131], v[94:95] op_sel:[1,0,0]
	v_pk_fma_f32 v[32:33], v[118:119], v[130:131], v[32:33] op_sel_hi:[0,1,1]
	v_pk_fma_f32 v[34:35], v[118:119], v[130:131], v[34:35] op_sel:[1,0,0]
	s_waitcnt lgkmcnt(0)
	v_pk_mul_f32 v[130:131], v[92:93], v[24:25] op_sel_hi:[1,0]
	v_pk_mul_f32 v[12:13], v[92:93], v[124:125] op_sel_hi:[1,0]
	v_pk_fma_f32 v[130:131], v[94:95], v[24:25], v[130:131] op_sel:[0,1,0]
	v_pk_fma_f32 v[12:13], v[94:95], v[124:125], v[12:13] op_sel:[0,1,0]
	v_pk_fma_f32 v[130:131], v[32:33], v[26:27], v[130:131] op_sel_hi:[1,0,1]
	v_pk_fma_f32 v[12:13], v[32:33], v[126:127], v[12:13] op_sel_hi:[1,0,1]
	v_pk_fma_f32 v[130:131], v[34:35], v[26:27], v[130:131] op_sel:[0,1,0]
	v_pk_fma_f32 v[12:13], v[34:35], v[126:127], v[12:13] op_sel:[0,1,0]
	v_cvt_pk_f16_f32 v12, v12, v13
	v_add_f32_dpp v130, v130, v130 quad_perm:[1,0,3,2] row_mask:0xf bank_mask:0xf bound_ctrl:1
	v_add_f32_dpp v131, v131, v131 quad_perm:[1,0,3,2] row_mask:0xf bank_mask:0xf bound_ctrl:1
	ds_write_b32 v47, v12 offset:7168
	v_pk_fma_f32 v[92:93], v[28:29], v[96:97], v[92:93] op_sel_hi:[0,1,1]
	v_add_f32_dpp v130, v130, v130 quad_perm:[2,3,0,1] row_mask:0xf bank_mask:0xf bound_ctrl:1
	v_add_f32_dpp v131, v131, v131 quad_perm:[2,3,0,1] row_mask:0xf bank_mask:0xf bound_ctrl:1
	v_pk_fma_f32 v[94:95], v[28:29], v[96:97], v[94:95] op_sel:[1,0,0]
	v_add_f32_dpp v130, v130, v130 row_half_mirror row_mask:0xf bank_mask:0xf bound_ctrl:1
	v_add_f32_dpp v131, v131, v131 row_half_mirror row_mask:0xf bank_mask:0xf bound_ctrl:1
	v_pk_fma_f32 v[32:33], v[30:31], v[96:97], v[32:33] op_sel_hi:[0,1,1]
	v_pk_fma_f32 v[34:35], v[30:31], v[96:97], v[34:35] op_sel:[1,0,0]
	ds_read_b64 v[96:97], v115 offset:21760
	ds_read_b128 v[12:15], v113 offset:14336
	ds_read_b128 v[116:119], v113 offset:18432
	ds_read_b128 v[120:123], v113 offset:10240
	ds_read_b128 v[124:127], v113 offset:2048
	ds_read_b64 v[90:91], v112 offset:1024
	v_add_f32_dpp v130, v130, v130 row_mirror row_mask:0xf bank_mask:0xf bound_ctrl:1
	v_add_f32_dpp v131, v131, v131 row_mirror row_mask:0xf bank_mask:0xf bound_ctrl:1
	v_pk_fma_f32 v[92:93], v[20:21], v[130:131], v[92:93] op_sel_hi:[0,1,1]
	v_pk_fma_f32 v[94:95], v[20:21], v[130:131], v[94:95] op_sel:[1,0,0]
	v_pk_fma_f32 v[32:33], v[22:23], v[130:131], v[32:33] op_sel_hi:[0,1,1]
	v_pk_fma_f32 v[34:35], v[22:23], v[130:131], v[34:35] op_sel:[1,0,0]
	s_waitcnt lgkmcnt(4)
	v_pk_mul_f32 v[130:131], v[92:93], v[12:13] op_sel_hi:[1,0]
	v_pk_mul_f32 v[20:21], v[92:93], v[16:17] op_sel_hi:[1,0]
	v_pk_fma_f32 v[130:131], v[94:95], v[12:13], v[130:131] op_sel:[0,1,0]
	v_pk_fma_f32 v[20:21], v[94:95], v[16:17], v[20:21] op_sel:[0,1,0]
	v_pk_fma_f32 v[130:131], v[32:33], v[14:15], v[130:131] op_sel_hi:[1,0,1]
	v_pk_fma_f32 v[20:21], v[32:33], v[18:19], v[20:21] op_sel_hi:[1,0,1]
	v_pk_fma_f32 v[130:131], v[34:35], v[14:15], v[130:131] op_sel:[0,1,0]
	v_pk_fma_f32 v[20:21], v[34:35], v[18:19], v[20:21] op_sel:[0,1,0]
	v_cvt_pk_f16_f32 v20, v20, v21
	v_add_f32_dpp v130, v130, v130 quad_perm:[1,0,3,2] row_mask:0xf bank_mask:0xf bound_ctrl:1
	v_add_f32_dpp v131, v131, v131 quad_perm:[1,0,3,2] row_mask:0xf bank_mask:0xf bound_ctrl:1
	ds_write_b32 v47, v20 offset:8192
	ds_read_b128 v[24:27], v114 offset:14848
	ds_read_b128 v[20:23], v114 offset:18944
	ds_read_b128 v[28:31], v114 offset:10752
	ds_read_b128 v[16:19], v114 offset:2560
	s_waitcnt lgkmcnt(5)
	v_pk_fma_f32 v[92:93], v[120:121], v[90:91], v[92:93] op_sel_hi:[0,1,1]
	v_add_f32_dpp v130, v130, v130 quad_perm:[2,3,0,1] row_mask:0xf bank_mask:0xf bound_ctrl:1
	v_add_f32_dpp v131, v131, v131 quad_perm:[2,3,0,1] row_mask:0xf bank_mask:0xf bound_ctrl:1
	v_pk_fma_f32 v[94:95], v[120:121], v[90:91], v[94:95] op_sel:[1,0,0]
	v_add_f32_dpp v130, v130, v130 row_half_mirror row_mask:0xf bank_mask:0xf bound_ctrl:1
	v_add_f32_dpp v131, v131, v131 row_half_mirror row_mask:0xf bank_mask:0xf bound_ctrl:1
	v_pk_fma_f32 v[32:33], v[122:123], v[90:91], v[32:33] op_sel_hi:[0,1,1]
	v_pk_fma_f32 v[34:35], v[122:123], v[90:91], v[34:35] op_sel:[1,0,0]
	v_add_f32_dpp v130, v130, v130 row_mirror row_mask:0xf bank_mask:0xf bound_ctrl:1
	v_add_f32_dpp v131, v131, v131 row_mirror row_mask:0xf bank_mask:0xf bound_ctrl:1
	v_pk_fma_f32 v[92:93], v[116:117], v[130:131], v[92:93] op_sel_hi:[0,1,1]
	v_pk_fma_f32 v[94:95], v[116:117], v[130:131], v[94:95] op_sel:[1,0,0]
	v_pk_fma_f32 v[32:33], v[118:119], v[130:131], v[32:33] op_sel_hi:[0,1,1]
	v_pk_fma_f32 v[34:35], v[118:119], v[130:131], v[34:35] op_sel:[1,0,0]
	s_waitcnt lgkmcnt(0)
	v_pk_mul_f32 v[130:131], v[92:93], v[24:25] op_sel_hi:[1,0]
	v_pk_mul_f32 v[12:13], v[92:93], v[124:125] op_sel_hi:[1,0]
	v_pk_fma_f32 v[130:131], v[94:95], v[24:25], v[130:131] op_sel:[0,1,0]
	v_pk_fma_f32 v[12:13], v[94:95], v[124:125], v[12:13] op_sel:[0,1,0]
	v_pk_fma_f32 v[130:131], v[32:33], v[26:27], v[130:131] op_sel_hi:[1,0,1]
	v_pk_fma_f32 v[12:13], v[32:33], v[126:127], v[12:13] op_sel_hi:[1,0,1]
	v_pk_fma_f32 v[130:131], v[34:35], v[26:27], v[130:131] op_sel:[0,1,0]
	v_pk_fma_f32 v[12:13], v[34:35], v[126:127], v[12:13] op_sel:[0,1,0]
	v_cvt_pk_f16_f32 v12, v12, v13
	v_add_f32_dpp v130, v130, v130 quad_perm:[1,0,3,2] row_mask:0xf bank_mask:0xf bound_ctrl:1
	v_add_f32_dpp v131, v131, v131 quad_perm:[1,0,3,2] row_mask:0xf bank_mask:0xf bound_ctrl:1
	ds_write_b32 v47, v12 offset:9216
	v_pk_fma_f32 v[92:93], v[28:29], v[96:97], v[92:93] op_sel_hi:[0,1,1]
	v_add_f32_dpp v130, v130, v130 quad_perm:[2,3,0,1] row_mask:0xf bank_mask:0xf bound_ctrl:1
	v_add_f32_dpp v131, v131, v131 quad_perm:[2,3,0,1] row_mask:0xf bank_mask:0xf bound_ctrl:1
	v_pk_fma_f32 v[94:95], v[28:29], v[96:97], v[94:95] op_sel:[1,0,0]
	v_add_f32_dpp v130, v130, v130 row_half_mirror row_mask:0xf bank_mask:0xf bound_ctrl:1
	v_add_f32_dpp v131, v131, v131 row_half_mirror row_mask:0xf bank_mask:0xf bound_ctrl:1
	v_pk_fma_f32 v[32:33], v[30:31], v[96:97], v[32:33] op_sel_hi:[0,1,1]
	v_pk_fma_f32 v[34:35], v[30:31], v[96:97], v[34:35] op_sel:[1,0,0]
	ds_read_b64 v[96:97], v115 offset:22016
	ds_read_b128 v[12:15], v113 offset:14848
	ds_read_b128 v[116:119], v113 offset:18944
	ds_read_b128 v[120:123], v113 offset:10752
	ds_read_b128 v[124:127], v113 offset:2560
	ds_read_b64 v[90:91], v112 offset:1280
	v_add_f32_dpp v130, v130, v130 row_mirror row_mask:0xf bank_mask:0xf bound_ctrl:1
	v_add_f32_dpp v131, v131, v131 row_mirror row_mask:0xf bank_mask:0xf bound_ctrl:1
	v_pk_fma_f32 v[92:93], v[20:21], v[130:131], v[92:93] op_sel_hi:[0,1,1]
	v_pk_fma_f32 v[94:95], v[20:21], v[130:131], v[94:95] op_sel:[1,0,0]
	v_pk_fma_f32 v[32:33], v[22:23], v[130:131], v[32:33] op_sel_hi:[0,1,1]
	v_pk_fma_f32 v[34:35], v[22:23], v[130:131], v[34:35] op_sel:[1,0,0]
	s_waitcnt lgkmcnt(4)
	v_pk_mul_f32 v[130:131], v[92:93], v[12:13] op_sel_hi:[1,0]
	v_pk_mul_f32 v[20:21], v[92:93], v[16:17] op_sel_hi:[1,0]
	v_pk_fma_f32 v[130:131], v[94:95], v[12:13], v[130:131] op_sel:[0,1,0]
	v_pk_fma_f32 v[20:21], v[94:95], v[16:17], v[20:21] op_sel:[0,1,0]
	v_pk_fma_f32 v[130:131], v[32:33], v[14:15], v[130:131] op_sel_hi:[1,0,1]
	v_pk_fma_f32 v[20:21], v[32:33], v[18:19], v[20:21] op_sel_hi:[1,0,1]
	v_pk_fma_f32 v[130:131], v[34:35], v[14:15], v[130:131] op_sel:[0,1,0]
	v_pk_fma_f32 v[20:21], v[34:35], v[18:19], v[20:21] op_sel:[0,1,0]
	v_cvt_pk_f16_f32 v20, v20, v21
	v_add_f32_dpp v130, v130, v130 quad_perm:[1,0,3,2] row_mask:0xf bank_mask:0xf bound_ctrl:1
	v_add_f32_dpp v131, v131, v131 quad_perm:[1,0,3,2] row_mask:0xf bank_mask:0xf bound_ctrl:1
	ds_write_b32 v47, v20 offset:10240
	ds_read_b128 v[24:27], v114 offset:15360
	ds_read_b128 v[20:23], v114 offset:19456
	ds_read_b128 v[28:31], v114 offset:11264
	ds_read_b128 v[16:19], v114 offset:3072
	s_waitcnt lgkmcnt(5)
	v_pk_fma_f32 v[92:93], v[120:121], v[90:91], v[92:93] op_sel_hi:[0,1,1]
	v_add_f32_dpp v130, v130, v130 quad_perm:[2,3,0,1] row_mask:0xf bank_mask:0xf bound_ctrl:1
	v_add_f32_dpp v131, v131, v131 quad_perm:[2,3,0,1] row_mask:0xf bank_mask:0xf bound_ctrl:1
	v_pk_fma_f32 v[94:95], v[120:121], v[90:91], v[94:95] op_sel:[1,0,0]
	v_add_f32_dpp v130, v130, v130 row_half_mirror row_mask:0xf bank_mask:0xf bound_ctrl:1
	v_add_f32_dpp v131, v131, v131 row_half_mirror row_mask:0xf bank_mask:0xf bound_ctrl:1
	v_pk_fma_f32 v[32:33], v[122:123], v[90:91], v[32:33] op_sel_hi:[0,1,1]
	v_pk_fma_f32 v[34:35], v[122:123], v[90:91], v[34:35] op_sel:[1,0,0]
	v_add_f32_dpp v130, v130, v130 row_mirror row_mask:0xf bank_mask:0xf bound_ctrl:1
	v_add_f32_dpp v131, v131, v131 row_mirror row_mask:0xf bank_mask:0xf bound_ctrl:1
	v_pk_fma_f32 v[92:93], v[116:117], v[130:131], v[92:93] op_sel_hi:[0,1,1]
	v_pk_fma_f32 v[94:95], v[116:117], v[130:131], v[94:95] op_sel:[1,0,0]
	v_pk_fma_f32 v[32:33], v[118:119], v[130:131], v[32:33] op_sel_hi:[0,1,1]
	v_pk_fma_f32 v[34:35], v[118:119], v[130:131], v[34:35] op_sel:[1,0,0]
	s_waitcnt lgkmcnt(0)
	v_pk_mul_f32 v[130:131], v[92:93], v[24:25] op_sel_hi:[1,0]
	v_pk_mul_f32 v[12:13], v[92:93], v[124:125] op_sel_hi:[1,0]
	v_pk_fma_f32 v[130:131], v[94:95], v[24:25], v[130:131] op_sel:[0,1,0]
	v_pk_fma_f32 v[12:13], v[94:95], v[124:125], v[12:13] op_sel:[0,1,0]
	v_pk_fma_f32 v[130:131], v[32:33], v[26:27], v[130:131] op_sel_hi:[1,0,1]
	v_pk_fma_f32 v[12:13], v[32:33], v[126:127], v[12:13] op_sel_hi:[1,0,1]
	v_pk_fma_f32 v[130:131], v[34:35], v[26:27], v[130:131] op_sel:[0,1,0]
	v_pk_fma_f32 v[12:13], v[34:35], v[126:127], v[12:13] op_sel:[0,1,0]
	v_cvt_pk_f16_f32 v12, v12, v13
	v_add_f32_dpp v130, v130, v130 quad_perm:[1,0,3,2] row_mask:0xf bank_mask:0xf bound_ctrl:1
	v_add_f32_dpp v131, v131, v131 quad_perm:[1,0,3,2] row_mask:0xf bank_mask:0xf bound_ctrl:1
	ds_write_b32 v47, v12 offset:11264
	v_pk_fma_f32 v[92:93], v[28:29], v[96:97], v[92:93] op_sel_hi:[0,1,1]
	v_add_f32_dpp v130, v130, v130 quad_perm:[2,3,0,1] row_mask:0xf bank_mask:0xf bound_ctrl:1
	v_add_f32_dpp v131, v131, v131 quad_perm:[2,3,0,1] row_mask:0xf bank_mask:0xf bound_ctrl:1
	v_pk_fma_f32 v[94:95], v[28:29], v[96:97], v[94:95] op_sel:[1,0,0]
	v_add_f32_dpp v130, v130, v130 row_half_mirror row_mask:0xf bank_mask:0xf bound_ctrl:1
	v_add_f32_dpp v131, v131, v131 row_half_mirror row_mask:0xf bank_mask:0xf bound_ctrl:1
	v_pk_fma_f32 v[32:33], v[30:31], v[96:97], v[32:33] op_sel_hi:[0,1,1]
	v_pk_fma_f32 v[34:35], v[30:31], v[96:97], v[34:35] op_sel:[1,0,0]
	ds_read_b64 v[96:97], v115 offset:22272
	ds_read_b128 v[12:15], v113 offset:15360
	ds_read_b128 v[116:119], v113 offset:19456
	ds_read_b128 v[120:123], v113 offset:11264
	ds_read_b128 v[124:127], v113 offset:3072
	ds_read_b64 v[90:91], v112 offset:1536
	v_add_f32_dpp v130, v130, v130 row_mirror row_mask:0xf bank_mask:0xf bound_ctrl:1
	v_add_f32_dpp v131, v131, v131 row_mirror row_mask:0xf bank_mask:0xf bound_ctrl:1
	v_pk_fma_f32 v[92:93], v[20:21], v[130:131], v[92:93] op_sel_hi:[0,1,1]
	v_pk_fma_f32 v[94:95], v[20:21], v[130:131], v[94:95] op_sel:[1,0,0]
	v_pk_fma_f32 v[32:33], v[22:23], v[130:131], v[32:33] op_sel_hi:[0,1,1]
	v_pk_fma_f32 v[34:35], v[22:23], v[130:131], v[34:35] op_sel:[1,0,0]
	s_waitcnt lgkmcnt(4)
	v_pk_mul_f32 v[130:131], v[92:93], v[12:13] op_sel_hi:[1,0]
	v_pk_mul_f32 v[20:21], v[92:93], v[16:17] op_sel_hi:[1,0]
	v_pk_fma_f32 v[130:131], v[94:95], v[12:13], v[130:131] op_sel:[0,1,0]
	v_pk_fma_f32 v[20:21], v[94:95], v[16:17], v[20:21] op_sel:[0,1,0]
	v_pk_fma_f32 v[130:131], v[32:33], v[14:15], v[130:131] op_sel_hi:[1,0,1]
	v_pk_fma_f32 v[20:21], v[32:33], v[18:19], v[20:21] op_sel_hi:[1,0,1]
	v_pk_fma_f32 v[130:131], v[34:35], v[14:15], v[130:131] op_sel:[0,1,0]
	v_pk_fma_f32 v[20:21], v[34:35], v[18:19], v[20:21] op_sel:[0,1,0]
	v_cvt_pk_f16_f32 v20, v20, v21
	v_add_f32_dpp v130, v130, v130 quad_perm:[1,0,3,2] row_mask:0xf bank_mask:0xf bound_ctrl:1
	v_add_f32_dpp v131, v131, v131 quad_perm:[1,0,3,2] row_mask:0xf bank_mask:0xf bound_ctrl:1
	ds_write_b32 v47, v20 offset:12288
	ds_read_b128 v[24:27], v114 offset:15872
	ds_read_b128 v[20:23], v114 offset:19968
	ds_read_b128 v[28:31], v114 offset:11776
	ds_read_b128 v[16:19], v114 offset:3584
	s_waitcnt lgkmcnt(5)
	v_pk_fma_f32 v[92:93], v[120:121], v[90:91], v[92:93] op_sel_hi:[0,1,1]
	v_add_f32_dpp v130, v130, v130 quad_perm:[2,3,0,1] row_mask:0xf bank_mask:0xf bound_ctrl:1
	v_add_f32_dpp v131, v131, v131 quad_perm:[2,3,0,1] row_mask:0xf bank_mask:0xf bound_ctrl:1
	v_pk_fma_f32 v[94:95], v[120:121], v[90:91], v[94:95] op_sel:[1,0,0]
	v_add_f32_dpp v130, v130, v130 row_half_mirror row_mask:0xf bank_mask:0xf bound_ctrl:1
	v_add_f32_dpp v131, v131, v131 row_half_mirror row_mask:0xf bank_mask:0xf bound_ctrl:1
	v_pk_fma_f32 v[32:33], v[122:123], v[90:91], v[32:33] op_sel_hi:[0,1,1]
	v_pk_fma_f32 v[34:35], v[122:123], v[90:91], v[34:35] op_sel:[1,0,0]
	v_add_f32_dpp v130, v130, v130 row_mirror row_mask:0xf bank_mask:0xf bound_ctrl:1
	v_add_f32_dpp v131, v131, v131 row_mirror row_mask:0xf bank_mask:0xf bound_ctrl:1
	v_pk_fma_f32 v[92:93], v[116:117], v[130:131], v[92:93] op_sel_hi:[0,1,1]
	v_pk_fma_f32 v[94:95], v[116:117], v[130:131], v[94:95] op_sel:[1,0,0]
	v_pk_fma_f32 v[32:33], v[118:119], v[130:131], v[32:33] op_sel_hi:[0,1,1]
	v_pk_fma_f32 v[34:35], v[118:119], v[130:131], v[34:35] op_sel:[1,0,0]
	s_waitcnt lgkmcnt(0)
	v_pk_mul_f32 v[130:131], v[92:93], v[24:25] op_sel_hi:[1,0]
	v_pk_mul_f32 v[12:13], v[92:93], v[124:125] op_sel_hi:[1,0]
	v_pk_fma_f32 v[130:131], v[94:95], v[24:25], v[130:131] op_sel:[0,1,0]
	v_pk_fma_f32 v[12:13], v[94:95], v[124:125], v[12:13] op_sel:[0,1,0]
	v_pk_fma_f32 v[130:131], v[32:33], v[26:27], v[130:131] op_sel_hi:[1,0,1]
	v_pk_fma_f32 v[12:13], v[32:33], v[126:127], v[12:13] op_sel_hi:[1,0,1]
	v_pk_fma_f32 v[130:131], v[34:35], v[26:27], v[130:131] op_sel:[0,1,0]
	v_pk_fma_f32 v[12:13], v[34:35], v[126:127], v[12:13] op_sel:[0,1,0]
	v_cvt_pk_f16_f32 v12, v12, v13
	v_add_f32_dpp v130, v130, v130 quad_perm:[1,0,3,2] row_mask:0xf bank_mask:0xf bound_ctrl:1
	v_add_f32_dpp v131, v131, v131 quad_perm:[1,0,3,2] row_mask:0xf bank_mask:0xf bound_ctrl:1
	ds_write_b32 v47, v12 offset:13312
	v_pk_fma_f32 v[92:93], v[28:29], v[96:97], v[92:93] op_sel_hi:[0,1,1]
	v_add_f32_dpp v130, v130, v130 quad_perm:[2,3,0,1] row_mask:0xf bank_mask:0xf bound_ctrl:1
	v_add_f32_dpp v131, v131, v131 quad_perm:[2,3,0,1] row_mask:0xf bank_mask:0xf bound_ctrl:1
	v_pk_fma_f32 v[94:95], v[28:29], v[96:97], v[94:95] op_sel:[1,0,0]
	v_add_f32_dpp v130, v130, v130 row_half_mirror row_mask:0xf bank_mask:0xf bound_ctrl:1
	v_add_f32_dpp v131, v131, v131 row_half_mirror row_mask:0xf bank_mask:0xf bound_ctrl:1
	v_pk_fma_f32 v[32:33], v[30:31], v[96:97], v[32:33] op_sel_hi:[0,1,1]
	v_pk_fma_f32 v[34:35], v[30:31], v[96:97], v[34:35] op_sel:[1,0,0]
	ds_read_b64 v[96:97], v115 offset:22272
	ds_read_b128 v[12:15], v113 offset:15872
	ds_read_b128 v[116:119], v113 offset:19968
	ds_read_b128 v[120:123], v113 offset:11776
	ds_read_b128 v[124:127], v113 offset:3584
	ds_read_b64 v[90:91], v112 offset:1792
	v_add_f32_dpp v130, v130, v130 row_mirror row_mask:0xf bank_mask:0xf bound_ctrl:1
	v_add_f32_dpp v131, v131, v131 row_mirror row_mask:0xf bank_mask:0xf bound_ctrl:1
	v_pk_fma_f32 v[92:93], v[20:21], v[130:131], v[92:93] op_sel_hi:[0,1,1]
	v_pk_fma_f32 v[94:95], v[20:21], v[130:131], v[94:95] op_sel:[1,0,0]
	v_pk_fma_f32 v[32:33], v[22:23], v[130:131], v[32:33] op_sel_hi:[0,1,1]
	v_pk_fma_f32 v[34:35], v[22:23], v[130:131], v[34:35] op_sel:[1,0,0]
	s_waitcnt lgkmcnt(4)
	v_pk_mul_f32 v[130:131], v[92:93], v[12:13] op_sel_hi:[1,0]
	v_pk_mul_f32 v[20:21], v[92:93], v[16:17] op_sel_hi:[1,0]
	v_pk_fma_f32 v[130:131], v[94:95], v[12:13], v[130:131] op_sel:[0,1,0]
	v_pk_fma_f32 v[20:21], v[94:95], v[16:17], v[20:21] op_sel:[0,1,0]
	v_pk_fma_f32 v[130:131], v[32:33], v[14:15], v[130:131] op_sel_hi:[1,0,1]
	v_pk_fma_f32 v[20:21], v[32:33], v[18:19], v[20:21] op_sel_hi:[1,0,1]
	v_pk_fma_f32 v[130:131], v[34:35], v[14:15], v[130:131] op_sel:[0,1,0]
	v_pk_fma_f32 v[20:21], v[34:35], v[18:19], v[20:21] op_sel:[0,1,0]
	v_cvt_pk_f16_f32 v20, v20, v21
	v_add_f32_dpp v130, v130, v130 quad_perm:[1,0,3,2] row_mask:0xf bank_mask:0xf bound_ctrl:1
	v_add_f32_dpp v131, v131, v131 quad_perm:[1,0,3,2] row_mask:0xf bank_mask:0xf bound_ctrl:1
	ds_write_b32 v47, v20 offset:14336
	ds_read_b128 v[24:27], v114 offset:15872
	ds_read_b128 v[20:23], v114 offset:19968
	ds_read_b128 v[28:31], v114 offset:11776
	ds_read_b128 v[16:19], v114 offset:3584
	s_waitcnt lgkmcnt(5)
	v_pk_fma_f32 v[92:93], v[120:121], v[90:91], v[92:93] op_sel_hi:[0,1,1]
	v_add_f32_dpp v130, v130, v130 quad_perm:[2,3,0,1] row_mask:0xf bank_mask:0xf bound_ctrl:1
	v_add_f32_dpp v131, v131, v131 quad_perm:[2,3,0,1] row_mask:0xf bank_mask:0xf bound_ctrl:1
	v_pk_fma_f32 v[94:95], v[120:121], v[90:91], v[94:95] op_sel:[1,0,0]
	v_add_f32_dpp v130, v130, v130 row_half_mirror row_mask:0xf bank_mask:0xf bound_ctrl:1
	v_add_f32_dpp v131, v131, v131 row_half_mirror row_mask:0xf bank_mask:0xf bound_ctrl:1
	v_pk_fma_f32 v[32:33], v[122:123], v[90:91], v[32:33] op_sel_hi:[0,1,1]
	v_pk_fma_f32 v[34:35], v[122:123], v[90:91], v[34:35] op_sel:[1,0,0]
	v_add_f32_dpp v130, v130, v130 row_mirror row_mask:0xf bank_mask:0xf bound_ctrl:1
	v_add_f32_dpp v131, v131, v131 row_mirror row_mask:0xf bank_mask:0xf bound_ctrl:1
	v_pk_fma_f32 v[92:93], v[116:117], v[130:131], v[92:93] op_sel_hi:[0,1,1]
	v_pk_fma_f32 v[94:95], v[116:117], v[130:131], v[94:95] op_sel:[1,0,0]
	v_pk_fma_f32 v[32:33], v[118:119], v[130:131], v[32:33] op_sel_hi:[0,1,1]
	v_pk_fma_f32 v[34:35], v[118:119], v[130:131], v[34:35] op_sel:[1,0,0]
	v_pk_mul_f32 v[12:13], v[92:93], v[124:125] op_sel_hi:[1,0]
	v_pk_fma_f32 v[12:13], v[94:95], v[124:125], v[12:13] op_sel:[0,1,0]
	v_pk_fma_f32 v[12:13], v[32:33], v[126:127], v[12:13] op_sel_hi:[1,0,1]
	v_pk_fma_f32 v[12:13], v[34:35], v[126:127], v[12:13] op_sel:[0,1,0]
	v_cvt_pk_f16_f32 v12, v12, v13
	ds_write_b32 v47, v12 offset:15360
	v_swap_b32 v93, v94
	v_swap_b32 v33, v34
	ds_read_b128 v[12:15], v114 offset:7936
	s_add_i32 s93, s93, 3
	s_and_b64 vcc, exec, s[82:83]
	s_cbranch_vccz .LBB0_409
	s_waitcnt lgkmcnt(4)
	v_cvt_f32_f16_sdwa v29, v50 dst_sel:DWORD dst_unused:UNUSED_PAD src0_sel:WORD_1
	v_cvt_f32_f16_e32 v28, v50
	v_cvt_f32_f16_sdwa v31, v51 dst_sel:DWORD dst_unused:UNUSED_PAD src0_sel:WORD_1
	v_cvt_f32_f16_e32 v30, v51
	s_waitcnt lgkmcnt(3)
	v_cvt_f32_f16_sdwa v17, v56 dst_sel:DWORD dst_unused:UNUSED_PAD src0_sel:WORD_1
	v_cvt_f32_f16_e32 v16, v56
	v_cvt_f32_f16_sdwa v19, v57 dst_sel:DWORD dst_unused:UNUSED_PAD src0_sel:WORD_1
	v_cvt_f32_f16_e32 v18, v57
	v_pk_mul_f32 v[22:23], v[0:1], v[28:29]
	v_pk_mul_f32 v[20:21], v[2:3], v[30:31]
	s_waitcnt lgkmcnt(2)
	v_pk_mul_f32 v[96:97], v[22:23], v[22:23]
	v_pk_mul_f32 v[90:91], v[20:21], v[20:21]
	v_add_f32_e32 v42, v96, v97
	v_cvt_f32_f16_sdwa v25, v48 dst_sel:DWORD dst_unused:UNUSED_PAD src0_sel:WORD_1
	v_cvt_f32_f16_e32 v24, v48
	v_cvt_f32_f16_sdwa v27, v49 dst_sel:DWORD dst_unused:UNUSED_PAD src0_sel:WORD_1
	v_cvt_f32_f16_e32 v26, v49
	v_add_f32_e32 v42, v90, v42
	v_add_f32_e32 v42, v91, v42
	v_pk_add_f32 v[90:91], v[16:17], -1.0 op_sel_hi:[1,0]
	v_pk_add_f32 v[96:97], v[18:19], -1.0 op_sel_hi:[1,0]
	v_pk_fma_f32 v[90:91], v[4:5], v[90:91], 1.0 op_sel_hi:[1,1,0]
	v_pk_fma_f32 v[96:97], v[6:7], v[96:97], 1.0 op_sel_hi:[1,1,0]
	v_pk_mul_f32 v[90:91], v[28:29], v[90:91]
	v_pk_mul_f32 v[96:97], v[30:31], v[96:97]
	v_pk_mul_f32 v[28:29], v[24:25], v[90:91]
	v_pk_mul_f32 v[30:31], v[26:27], v[96:97]
	v_pk_mul_f32 v[28:29], v[8:9], v[28:29]
	v_pk_mul_f32 v[30:31], v[10:11], v[30:31]
	v_add_f32_e32 v28, v28, v29
	v_add_f32_e32 v29, v30, v31
	v_add_f32_e32 v28, v28, v29
	v_add_f32_dpp v42, v42, v42 quad_perm:[1,0,3,2] row_mask:0xf bank_mask:0xf bound_ctrl:1
	s_nop 0
	v_add_f32_dpp v28, v28, v28 quad_perm:[1,0,3,2] row_mask:0xf bank_mask:0xf bound_ctrl:1
	v_add_f32_dpp v42, v42, v42 quad_perm:[2,3,0,1] row_mask:0xf bank_mask:0xf bound_ctrl:1
	s_nop 0
	v_add_f32_dpp v28, v28, v28 quad_perm:[2,3,0,1] row_mask:0xf bank_mask:0xf bound_ctrl:1
	v_add_f32_dpp v42, v42, v42 row_half_mirror row_mask:0xf bank_mask:0xf bound_ctrl:1
	s_nop 0
	v_add_f32_dpp v28, v28, v28 row_half_mirror row_mask:0xf bank_mask:0xf bound_ctrl:1
	v_mov_b32_dpp v47, v42 row_mirror row_mask:0xf bank_mask:0xf bound_ctrl:1
	s_nop 0
	v_mov_b32_dpp v29, v28 row_mirror row_mask:0xf bank_mask:0xf bound_ctrl:1
	s_and_saveexec_b64 s[12:13], s[6:7]
	s_cbranch_execz .LBB0_442
	s_add_i32 s94, s94, 48
	v_cmp_lt_u32_e32 vcc, s94, v106
	s_and_b64 exec, exec, vcc
	s_cbranch_execz .LBB0_442
	v_add_f32_e32 v30, v28, v29
	v_add_u32_e32 v28, s94, v46
	v_ashrrev_i32_e32 v29, 31, v28
	v_lshlrev_b64 v[28:29], 6, v[28:29]
	v_lshl_add_u64 v[28:29], s[58:59], 0, v[28:29]
	global_store_dword v[28:29], v30, off
